# dense attention: redundant +0 row-sum initialisers removed (bit-identical); dead pad keeps the loop header at the same byte phase
# baseline (speedup 1.0000x reference)
; DEVI unsigned pk2(float lo, float hi) { const f32x2_t v = {lo, hi}; const bf16x2_t b = __builtin_convertvector(v, bf16x2_t); return __builtin_bit_cast(unsigned, b); }
; template <int DK, int QB, bool NA>
; DEVI void attn_item(const AttnArgs& a, unsigned char* smem) {
;     ...
;           f32x2 ls2 = {0.f, 0.f};
;           unsigned pw[2][4];
; #pragma unroll
;           for (int kb = 0; kb < 4; ++kb)
; #pragma unroll
;             for (int h = 0; h < 2; ++h) {
;               const f32x2 pe = {__builtin_amdgcn_exp2f(t[kb][h].x), __builtin_amdgcn_exp2f(t[kb][h].y)};
;               ls2 += pe;
;               pw[kb >> 1][(kb & 1) * 2 + h] = pk2(pe.x, pe.y);
;             }
;           l[qb] += ls2.x + ls2.y;
; #pragma unroll
;           for (int c = 0; c < 2; ++c) {
;             const u32x4 pv = (u32x4){pw[c][0], pw[c][1], pw[c][2], pw[c][3]};
;             pf[qb][c] = __builtin_bit_cast(bf16x8, pv);
;           }
;         }
;     ...
;       asm volatile("s_waitcnt lgkmcnt(0)"
;                    : "+v"(va[0][0]), "+v"(va[0][1]), "+v"(va[0][2]), "+v"(va[0][3]), "+v"(va[1][0]), "+v"(va[1][1]), "+v"(va[1][2]), "+v"(va[1][3]),
;                      "+v"(vbq[0][0]), "+v"(vbq[0][1]), "+v"(vbq[0][2]), "+v"(vbq[0][3]), "+v"(vbq[1][0]), "+v"(vbq[1][1]), "+v"(vbq[1][2]), "+v"(vbq[1][3])
;                    :: "memory");
;       __builtin_amdgcn_sched_barrier(0);
; #pragma unroll
;       for (int c = 0; c < 2; ++c)
; #pragma unroll
;         for (int db = 0; db < 4; ++db) {
;           const u32x4 vw = (u32x4){va[c][db].x, va[c][db].y, vbq[c][db].x, vbq[c][db].y};
;           const bf16x8 vf = __builtin_bit_cast(bf16x8, vw);
; #pragma unroll
;           for (int qb = 0; qb < QB; ++qb) o[db][qb] = __builtin_amdgcn_mfma_f32_16x16x32_bf16(vf, pf[qb][c], o[db][qb], 0, 0, 0);
;         }
.LBB0_2266:
	s_or_b64 exec, exec, s[42:43]
	s_mov_b32 s3, 1
	s_mov_b32 s9, 2
	s_movk_i32 s44, 0xc0
	s_waitcnt vmcnt(0)
	s_branch .LBB0_2269
	.p2align	6
	s_nop 0
	s_nop 0
	s_nop 0
	s_nop 0
.LBB0_2267:
	v_exp_f32_e32 v86, v122
	v_exp_f32_e32 v87, v123
	v_exp_f32_e32 v122, v120
	v_exp_f32_e32 v123, v121
	v_exp_f32_e32 v116, v116
	v_exp_f32_e32 v117, v117
	v_exp_f32_e32 v118, v118
	v_exp_f32_e32 v119, v119
	v_cvt_pk_bf16_f32 v120, v86, v87
	v_add_f32_e32 v86, v122, v86
	v_add_f32_e32 v87, v123, v87
	v_exp_f32_e32 v114, v114
	v_exp_f32_e32 v115, v115
	v_cvt_pk_bf16_f32 v121, v122, v123
	v_add_f32_e32 v86, v116, v86
	v_add_f32_e32 v87, v117, v87
	v_cvt_pk_bf16_f32 v122, v116, v117
	v_exp_f32_e32 v116, v112
	v_exp_f32_e32 v117, v113
	v_exp_f32_e32 v110, v110
	v_exp_f32_e32 v111, v111
	v_add_f32_e32 v86, v118, v86
	v_add_f32_e32 v87, v119, v87
	v_exp_f32_e32 v2, v2
	v_exp_f32_e32 v3, v3
	v_add_f32_e32 v86, v114, v86
	v_add_f32_e32 v87, v115, v87
	v_cvt_pk_bf16_f32 v112, v114, v115
	v_add_f32_e32 v86, v116, v86
	v_add_f32_e32 v87, v117, v87
	v_cvt_pk_bf16_f32 v115, v2, v3
	v_add_f32_e32 v86, v110, v86
	v_add_f32_e32 v87, v111, v87
	v_exp_f32_e32 v96, v96
	v_add_f32_e32 v86, v2, v86
	v_add_f32_e32 v87, v3, v87
	v_exp_f32_e32 v2, v124
	v_exp_f32_e32 v3, v125
	v_add_f32_e32 v0, v86, v87
	v_exp_f32_e32 v86, v98
	v_exp_f32_e32 v87, v99
	v_exp_f32_e32 v97, v97
	v_exp_f32_e32 v94, v94
	v_exp_f32_e32 v95, v95
	v_cvt_pk_bf16_f32 v113, v116, v117
	v_cvt_pk_bf16_f32 v116, v2, v3
	v_add_f32_e32 v2, v86, v2
	v_add_f32_e32 v3, v87, v3
	v_cvt_pk_bf16_f32 v117, v86, v87
	v_exp_f32_e32 v86, v92
	v_exp_f32_e32 v87, v93
	v_exp_f32_e32 v90, v90
	v_exp_f32_e32 v91, v91
	v_add_f32_e32 v2, v96, v2
	v_add_f32_e32 v3, v97, v3
	v_exp_f32_e32 v88, v88
	v_exp_f32_e32 v89, v89
	v_add_f32_e32 v2, v94, v2
	v_add_f32_e32 v3, v95, v3
	v_exp_f32_e32 v84, v84
	v_exp_f32_e32 v85, v85
	v_add_f32_e32 v2, v86, v2
	v_add_f32_e32 v3, v87, v3
	s_waitcnt lgkmcnt(0)
	v_add_f32_e32 v101, v101, v0
	v_add_f32_e32 v2, v90, v2
	v_add_f32_e32 v3, v91, v3
	v_cvt_pk_bf16_f32 v123, v118, v119
	v_add_f32_e32 v2, v88, v2
	v_add_f32_e32 v3, v89, v3
	v_cvt_pk_bf16_f32 v114, v110, v111
	v_add_f32_e32 v2, v84, v2
	v_add_f32_e32 v3, v85, v3
	v_cvt_pk_bf16_f32 v118, v96, v97
	v_add_f32_e32 v0, v2, v3
	v_add_f32_e32 v100, v100, v0
	v_cvt_pk_bf16_f32 v119, v94, v95
	v_cvt_pk_bf16_f32 v86, v86, v87
	v_cvt_pk_bf16_f32 v87, v90, v91
	v_cvt_pk_bf16_f32 v88, v88, v89
	v_cvt_pk_bf16_f32 v89, v84, v85
	s_setprio 1
	v_mfma_f32_16x16x32_bf16 v[48:51], v[80:83], v[120:123], v[48:51]
	v_mfma_f32_16x16x32_bf16 v[44:47], v[80:83], v[116:119], v[44:47]
	v_mfma_f32_16x16x32_bf16 v[40:43], v[76:79], v[120:123], v[40:43]
	v_mfma_f32_16x16x32_bf16 v[36:39], v[76:79], v[116:119], v[36:39]
	v_mfma_f32_16x16x32_bf16 v[32:35], v[72:75], v[120:123], v[32:35]
	v_mfma_f32_16x16x32_bf16 v[28:31], v[72:75], v[116:119], v[28:31]
	v_mfma_f32_16x16x32_bf16 v[24:27], v[68:71], v[120:123], v[24:27]
	v_mfma_f32_16x16x32_bf16 v[20:23], v[68:71], v[116:119], v[20:23]
	v_mfma_f32_16x16x32_bf16 v[48:51], v[64:67], v[112:115], v[48:51]
	v_mfma_f32_16x16x32_bf16 v[44:47], v[64:67], v[86:89], v[44:47]
	v_mfma_f32_16x16x32_bf16 v[40:43], v[60:63], v[112:115], v[40:43]
	v_mfma_f32_16x16x32_bf16 v[36:39], v[60:63], v[86:89], v[36:39]
	v_mfma_f32_16x16x32_bf16 v[32:35], v[56:59], v[112:115], v[32:35]
	v_mfma_f32_16x16x32_bf16 v[28:31], v[56:59], v[86:89], v[28:31]
	v_mfma_f32_16x16x32_bf16 v[24:27], v[52:55], v[112:115], v[24:27]
	v_mfma_f32_16x16x32_bf16 v[20:23], v[52:55], v[86:89], v[20:23]
	s_setprio 0

; DEVI unsigned pk2(float lo, float hi) { const f32x2_t v = {lo, hi}; const bf16x2_t b = __builtin_convertvector(v, bf16x2_t); return __builtin_bit_cast(unsigned, b); }
; template <int DK, int QB, bool NA>
; DEVI void attn_item(const AttnArgs& a, unsigned char* smem) {
;     ...
;           f32x2 ls2 = {0.f, 0.f};
;           unsigned pw[2][4];
; #pragma unroll
;           for (int kb = 0; kb < 4; ++kb)
; #pragma unroll
;             for (int h = 0; h < 2; ++h) {
;               const f32x2 pe = {__builtin_amdgcn_exp2f(t[kb][h].x), __builtin_amdgcn_exp2f(t[kb][h].y)};
;               ls2 += pe;
;               pw[kb >> 1][(kb & 1) * 2 + h] = pk2(pe.x, pe.y);
;             }
;           l[qb] += ls2.x + ls2.y;
; #pragma unroll
;           for (int c = 0; c < 2; ++c) {
;             const u32x4 pv = (u32x4){pw[c][0], pw[c][1], pw[c][2], pw[c][3]};
;             pf[qb][c] = __builtin_bit_cast(bf16x8, pv);
;           }
;         }
;     ...
;       asm volatile("s_waitcnt lgkmcnt(0)"
;                    : "+v"(va[0][0]), "+v"(va[0][1]), "+v"(va[0][2]), "+v"(va[0][3]), "+v"(va[1][0]), "+v"(va[1][1]), "+v"(va[1][2]), "+v"(va[1][3]),
;                      "+v"(vbq[0][0]), "+v"(vbq[0][1]), "+v"(vbq[0][2]), "+v"(vbq[0][3]), "+v"(vbq[1][0]), "+v"(vbq[1][1]), "+v"(vbq[1][2]), "+v"(vbq[1][3])
;                    :: "memory");
;       __builtin_amdgcn_sched_barrier(0);
; #pragma unroll
;       for (int c = 0; c < 2; ++c)
; #pragma unroll
;         for (int db = 0; db < 4; ++db) {
;           const u32x4 vw = (u32x4){va[c][db].x, va[c][db].y, vbq[c][db].x, vbq[c][db].y};
;           const bf16x8 vf = __builtin_bit_cast(bf16x8, vw);
; #pragma unroll
;           for (int qb = 0; qb < QB; ++qb) o[db][qb] = __builtin_amdgcn_mfma_f32_16x16x32_bf16(vf, pf[qb][c], o[db][qb], 0, 0, 0);
;         }
.LBB0_2297:
	v_exp_f32_e32 v86, v116
	v_exp_f32_e32 v87, v117
	v_exp_f32_e32 v116, v114
	v_exp_f32_e32 v117, v115
	v_exp_f32_e32 v110, v110
	v_exp_f32_e32 v111, v111
	v_exp_f32_e32 v112, v112
	v_exp_f32_e32 v113, v113
	v_cvt_pk_bf16_f32 v114, v86, v87
	v_add_f32_e32 v86, v116, v86
	v_add_f32_e32 v87, v117, v87
	v_exp_f32_e32 v108, v108
	v_exp_f32_e32 v109, v109
	v_cvt_pk_bf16_f32 v115, v116, v117
	v_add_f32_e32 v86, v110, v86
	v_add_f32_e32 v87, v111, v87
	v_cvt_pk_bf16_f32 v116, v110, v111
	v_exp_f32_e32 v110, v106
	v_exp_f32_e32 v111, v107
	v_exp_f32_e32 v104, v104
	v_exp_f32_e32 v105, v105
	v_add_f32_e32 v86, v112, v86
	v_add_f32_e32 v87, v113, v87
	v_exp_f32_e32 v2, v2
	v_exp_f32_e32 v3, v3
	v_add_f32_e32 v86, v108, v86
	v_add_f32_e32 v87, v109, v87
	v_cvt_pk_bf16_f32 v106, v108, v109
	v_add_f32_e32 v86, v110, v86
	v_add_f32_e32 v87, v111, v87
	v_cvt_pk_bf16_f32 v109, v2, v3
	v_add_f32_e32 v86, v104, v86
	v_add_f32_e32 v87, v105, v87
	v_exp_f32_e32 v96, v96
	v_add_f32_e32 v86, v2, v86
	v_add_f32_e32 v87, v3, v87
	v_exp_f32_e32 v2, v118
	v_exp_f32_e32 v3, v119
	v_add_f32_e32 v0, v86, v87
	v_exp_f32_e32 v86, v98
	v_exp_f32_e32 v87, v99
	v_exp_f32_e32 v97, v97
	v_exp_f32_e32 v94, v94
	v_exp_f32_e32 v95, v95
	v_cvt_pk_bf16_f32 v107, v110, v111
	v_cvt_pk_bf16_f32 v110, v2, v3
	v_add_f32_e32 v2, v86, v2
	v_add_f32_e32 v3, v87, v3
	v_cvt_pk_bf16_f32 v111, v86, v87
	v_exp_f32_e32 v86, v92
	v_exp_f32_e32 v87, v93
	v_exp_f32_e32 v90, v90
	v_exp_f32_e32 v91, v91
	v_add_f32_e32 v2, v96, v2
	v_add_f32_e32 v3, v97, v3
	v_exp_f32_e32 v88, v88
	v_exp_f32_e32 v89, v89
	v_add_f32_e32 v2, v94, v2
	v_add_f32_e32 v3, v95, v3
	v_exp_f32_e32 v84, v84
	v_exp_f32_e32 v85, v85
	v_add_f32_e32 v2, v86, v2
	v_add_f32_e32 v3, v87, v3
	s_waitcnt lgkmcnt(0)
	v_add_f32_e32 v101, v101, v0
	v_add_f32_e32 v2, v90, v2
	v_add_f32_e32 v3, v91, v3
	v_cvt_pk_bf16_f32 v117, v112, v113
	v_add_f32_e32 v2, v88, v2
	v_add_f32_e32 v3, v89, v3
	v_cvt_pk_bf16_f32 v108, v104, v105
	v_add_f32_e32 v2, v84, v2
	v_add_f32_e32 v3, v85, v3
	v_cvt_pk_bf16_f32 v112, v96, v97
	v_add_f32_e32 v0, v2, v3
	v_add_f32_e32 v100, v100, v0
	v_cvt_pk_bf16_f32 v113, v94, v95
	v_cvt_pk_bf16_f32 v86, v86, v87
	v_cvt_pk_bf16_f32 v87, v90, v91
	v_cvt_pk_bf16_f32 v88, v88, v89
	v_cvt_pk_bf16_f32 v89, v84, v85
	s_setprio 1
	v_mfma_f32_16x16x32_bf16 v[48:51], v[80:83], v[114:117], v[48:51]
	v_mfma_f32_16x16x32_bf16 v[44:47], v[80:83], v[110:113], v[44:47]
	v_mfma_f32_16x16x32_bf16 v[40:43], v[76:79], v[114:117], v[40:43]
	v_mfma_f32_16x16x32_bf16 v[36:39], v[76:79], v[110:113], v[36:39]
	v_mfma_f32_16x16x32_bf16 v[32:35], v[72:75], v[114:117], v[32:35]
	v_mfma_f32_16x16x32_bf16 v[28:31], v[72:75], v[110:113], v[28:31]
	v_mfma_f32_16x16x32_bf16 v[24:27], v[68:71], v[114:117], v[24:27]
	v_mfma_f32_16x16x32_bf16 v[20:23], v[68:71], v[110:113], v[20:23]
	v_mfma_f32_16x16x32_bf16 v[48:51], v[64:67], v[106:109], v[48:51]
	v_mfma_f32_16x16x32_bf16 v[44:47], v[64:67], v[86:89], v[44:47]
	v_mfma_f32_16x16x32_bf16 v[40:43], v[60:63], v[106:109], v[40:43]
	v_mfma_f32_16x16x32_bf16 v[36:39], v[60:63], v[86:89], v[36:39]
	v_mfma_f32_16x16x32_bf16 v[32:35], v[56:59], v[106:109], v[32:35]
	v_mfma_f32_16x16x32_bf16 v[28:31], v[56:59], v[86:89], v[28:31]
	v_mfma_f32_16x16x32_bf16 v[24:27], v[52:55], v[106:109], v[24:27]
	v_mfma_f32_16x16x32_bf16 v[20:23], v[52:55], v[86:89], v[20:23]
	s_setprio 0

; template <int DK, int QB, bool NA>
; DEVI void attn_item(const AttnArgs& a, unsigned char* smem) {
;     ...
;       const bool ismeta = (j == nt - 1);
;       bf16x8 pf[QB][2];
;       if constexpr (!NA) {
;         typedef float f32x2 __attribute__((ext_vector_type(2)));
; #pragma unroll
;         for (int qb = 0; qb < QB; ++qb) {
;           if (ismeta) {
; #pragma unroll
;             for (int kb = 1; kb < 4; ++kb) s[kb][qb] = (f32x4){-1e30f, -1e30f, -1e30f, -1e30f};
;           }
;           const f32x2 scv = {a.sc2, a.sc2}, nmv = {-m[qb], -m[qb]};
;           f32x2 t[4][2];
; #pragma unroll
;           for (int kb = 0; kb < 4; ++kb)
; #pragma unroll
;             for (int h = 0; h < 2; ++h) {
;               const f32x2 sv = {s[kb][qb][2 * h], s[kb][qb][2 * h + 1]};
;               t[kb][h] = sv * scv + nmv;
;             }
;           float mx = fmaxf(t[0][0].x, t[0][0].y);
; #pragma unroll
;           for (int kb = 0; kb < 4; ++kb)
; #pragma unroll
;             for (int h = 0; h < 2; ++h) mx = fmaxf(mx, fmaxf(t[kb][h].x, t[kb][h].y));
;           if (j == 0 || __any(mx > 6.f)) {
;             mx = xmax32(xmax16(mx));
;             const float d = (j == 0) ? mx : fmaxf(mx, 0.f);
;             const float alpha = __builtin_amdgcn_exp2f(-d);
;             const f32x2 dv = {d, d};
; #pragma unroll
;             for (int kb = 0; kb < 4; ++kb)
; #pragma unroll
;               for (int h = 0; h < 2; ++h) t[kb][h] -= dv;
;             m[qb] += d;
;             l[qb] *= alpha;
; #pragma unroll
;             for (int db = 0; db < 4; ++db) o[db][qb] *= alpha;
;           }
;           f32x2 ls2 = {0.f, 0.f};
;           unsigned pw[2][4];
; #pragma unroll
;           for (int kb = 0; kb < 4; ++kb)
; #pragma unroll
;             for (int h = 0; h < 2; ++h) {
;               const f32x2 pe = {__builtin_amdgcn_exp2f(t[kb][h].x), __builtin_amdgcn_exp2f(t[kb][h].y)};
;               ls2 += pe;
;               pw[kb >> 1][(kb & 1) * 2 + h] = pk2(pe.x, pe.y);
;             }
;           l[qb] += ls2.x + ls2.y;
; #pragma unroll
;           for (int c = 0; c < 2; ++c) {
;             const u32x4 pv = (u32x4){pw[c][0], pw[c][1], pw[c][2], pw[c][3]};
;             pf[qb][c] = __builtin_bit_cast(bf16x8, pv);
;           }
;         }
;     ...
;   if (wact) {
; #pragma unroll
;     for (int qb = 0; qb < QB; ++qb) {
;       const float lt = xsum32(xsum16(l[qb]));
.LBB0_2303:
	v_exp_f32_e32 v74, v74
	v_exp_f32_e32 v75, v75
	v_exp_f32_e32 v72, v72
	v_exp_f32_e32 v73, v73
	v_exp_f32_e32 v18, v18
	v_exp_f32_e32 v19, v19
	v_cvt_pk_bf16_f32 v78, v74, v75
	v_add_f32_e32 v74, v72, v74
	v_add_f32_e32 v75, v73, v75
	v_cvt_pk_bf16_f32 v79, v72, v73
	v_add_f32_e32 v72, v18, v74
	v_add_f32_e32 v73, v19, v75
	v_exp_f32_e32 v70, v70
	v_add_f32_e32 v72, v18, v72
	v_add_f32_e32 v73, v19, v73
	v_exp_f32_e32 v71, v71
	v_add_f32_e32 v72, v18, v72
	v_add_f32_e32 v73, v19, v73
	v_cvt_pk_bf16_f32 v80, v18, v19
	v_add_f32_e32 v72, v18, v72
	v_add_f32_e32 v73, v19, v73
	v_exp_f32_e32 v68, v68
	v_add_f32_e32 v72, v18, v72
	v_add_f32_e32 v73, v19, v73
	v_exp_f32_e32 v69, v69
	v_add_f32_e32 v18, v18, v72
	v_add_f32_e32 v19, v19, v73
	v_exp_f32_e32 v72, v76
	v_exp_f32_e32 v73, v77
	s_waitcnt lgkmcnt(0)
	v_add_f32_e32 v0, v18, v19
	v_add_f32_e32 v0, v101, v0
	v_cvt_pk_bf16_f32 v76, v70, v71
	v_mov_b32_e32 v81, v80
	v_mov_b32_e32 v82, v80
	v_mov_b32_e32 v83, v80
	v_mov_b32_e32 v84, v80
	v_mov_b32_e32 v85, v80
	v_cvt_pk_bf16_f32 v74, v68, v69
	v_cvt_pk_bf16_f32 v75, v72, v73
	v_mov_b32_e32 v77, v76
	v_mov_b32_e32 v86, v76
	v_mov_b32_e32 v87, v76
	v_mov_b32_e32 v88, v76
	v_mov_b32_e32 v89, v76
	s_setprio 1
	v_mfma_f32_16x16x32_bf16 v[40:43], v[60:63], v[78:81], v[40:43]
	v_mfma_f32_16x16x32_bf16 v[36:39], v[60:63], v[74:77], v[36:39]
	v_mfma_f32_16x16x32_bf16 v[48:51], v[64:67], v[78:81], v[48:51]
	v_mfma_f32_16x16x32_bf16 v[44:47], v[64:67], v[74:77], v[44:47]
	v_mfma_f32_16x16x32_bf16 v[60:63], v[56:59], v[78:81], v[32:35]
	v_mfma_f32_16x16x32_bf16 v[56:59], v[56:59], v[74:77], v[28:31]
	s_nop 1
	v_or_b32_e32 v35, v128, v126
	v_lshlrev_b32_e32 v34, 2, v127
	v_cmp_gt_i32_e32 vcc, s57, v35
	v_mfma_f32_16x16x32_bf16 v[26:29], v[52:55], v[78:81], v[24:27]
	v_mfma_f32_16x16x32_bf16 v[52:55], v[52:55], v[74:77], v[20:23]
	v_mfma_f32_16x16x32_bf16 v[22:25], v[10:13], v[82:85], v[40:43]
	v_mfma_f32_16x16x32_bf16 v[10:13], v[10:13], v[86:89], v[36:39]
	s_nop 2
	v_mov_b32_e32 v36, v0
	v_mfma_f32_16x16x32_bf16 v[30:33], v[14:17], v[82:85], v[48:51]
	s_nop 0
	v_permlane16_swap_b32_e32 v0, v36
	v_add_f32_e32 v36, v0, v36
	v_mfma_f32_16x16x32_bf16 v[14:17], v[14:17], v[86:89], v[44:47]
	v_mov_b32_e32 v37, v36
	s_nop 1
	v_permlane32_swap_b32_e32 v36, v37
	v_mfma_f32_16x16x32_bf16 v[18:21], v[6:9], v[82:85], v[60:63]
	v_lshlrev_b32_e32 v0, 1, v34
	v_mfma_f32_16x16x32_bf16 v[6:9], v[6:9], v[86:89], v[56:59]
	v_mfma_f32_16x16x32_bf16 v[26:29], v[2:5], v[82:85], v[26:29]
	v_mfma_f32_16x16x32_bf16 v[2:5], v[2:5], v[86:89], v[52:55]
	s_setprio 0
	s_and_saveexec_b64 s[0:1], vcc
	s_cbranch_execz .LBB0_2305
	v_add_f32_e32 v36, v36, v37
	v_div_scale_f32 v37, s[8:9], v36, v36, 1.0
	v_rcp_f32_e32 v38, v37
	v_div_scale_f32 v39, vcc, 1.0, v36, 1.0
	s_lshl_b32 s3, s58, 1
	v_fma_f32 v40, -v37, v38, 1.0
	v_fmac_f32_e32 v38, v40, v38
	v_mul_f32_e32 v40, v39, v38
	v_fma_f32 v41, -v37, v40, v39
	v_fmac_f32_e32 v40, v41, v38
	v_fma_f32 v37, -v37, v40, v39
	v_div_fmas_f32 v37, v37, v38, v40
	v_div_fixup_f32 v36, v37, v36, 1.0
	v_pk_mul_f32 v[32:33], v[32:33], v[36:37] op_sel_hi:[1,0]
	v_pk_mul_f32 v[30:31], v[30:31], v[36:37] op_sel_hi:[1,0]
	v_pk_mul_f32 v[20:21], v[20:21], v[36:37] op_sel_hi:[1,0]
	v_cvt_pk_bf16_f32 v30, v30, v31
	v_cvt_pk_bf16_f32 v31, v32, v33
	v_add_u32_e32 v32, s59, v35
	v_ashrrev_i32_e32 v33, 31, v32
	v_mad_u64_u32 v[38:39], s[8:9], s3, v206, v[32:33]
	v_pk_mul_f32 v[18:19], v[18:19], v[36:37] op_sel_hi:[1,0]
	s_or_b32 s3, s3, 1
	v_readlane_b32 s28, v251, 54
	v_cvt_pk_bf16_f32 v18, v18, v19
	v_cvt_pk_bf16_f32 v19, v20, v21
	v_mad_u64_u32 v[20:21], s[8:9], s3, v206, v[32:33]
	v_lshlrev_b64 v[38:39], 6, v[38:39]
	v_readlane_b32 s29, v251, 55
	v_lshlrev_b64 v[20:21], 6, v[20:21]
	v_pk_mul_f32 v[24:25], v[24:25], v[36:37] op_sel_hi:[1,0]
	v_lshl_add_u64 v[38:39], s[28:29], 0, v[38:39]
	v_pk_mul_f32 v[22:23], v[22:23], v[36:37] op_sel_hi:[1,0]
	v_lshl_add_u64 v[20:21], s[28:29], 0, v[20:21]
	v_lshl_add_u64 v[38:39], v[38:39], 0, v[0:1]
	v_cvt_pk_bf16_f32 v22, v22, v23
	v_cvt_pk_bf16_f32 v23, v24, v25
	v_lshl_add_u64 v[20:21], v[20:21], 0, v[0:1]
	global_store_dwordx2 v[38:39], v[22:23], off offset:32
	global_store_dwordx2 v[20:21], v[18:19], off
	v_pk_mul_f32 v[18:19], v[28:29], v[36:37] op_sel_hi:[1,0]
	v_pk_mul_f32 v[20:21], v[26:27], v[36:37] op_sel_hi:[1,0]
	v_or_b32_e32 v22, s56, v34
	v_cvt_pk_bf16_f32 v20, v20, v21
	v_cvt_pk_bf16_f32 v21, v18, v19
	v_or_b32_e32 v18, 48, v22
	v_lshrrev_b32_e32 v18, 5, v18
	v_mad_u64_u32 v[18:19], s[8:9], v18, s93, v[32:33]
	v_bitop3_b32 v22, v22, 28, 48 bitop3:0xc8
	v_lshlrev_b64 v[18:19], 6, v[18:19]
	v_lshl_add_u64 v[18:19], s[28:29], 0, v[18:19]
	v_lshlrev_b32_e32 v22, 1, v22
	v_mov_b32_e32 v23, v1
	v_lshl_add_u64 v[18:19], v[18:19], 0, v[22:23]
	global_store_dwordx2 v[38:39], v[30:31], off
	global_store_dwordx2 v[18:19], v[20:21], off
; DEVI unsigned pk2(float lo, float hi) { const f32x2_t v = {lo, hi}; const bf16x2_t b = __builtin_convertvector(v, bf16x2_t); return __builtin_bit_cast(unsigned, b); }
; DEVI size_t blk_off(int row, int col) { return ((size_t)(col >> 5) * MROWS + row) * 32 + (col & 31); }
; DEVI float xsum16(float x) { auto r = __builtin_amdgcn_permlane16_swap(__float_as_uint(x), __float_as_uint(x), false, false); return __uint_as_float(r[0]) + __uint_as_float(r[1]); }
; DEVI float xsum32(float x) { auto r = __builtin_amdgcn_permlane32_swap(__float_as_uint(x), __float_as_uint(x), false, false); return __uint_as_float(r[0]) + __uint_as_float(r[1]); }
; template <int DK, int QB, bool NA>
; DEVI void attn_item(const AttnArgs& a, unsigned char* smem) {
;     ...
;           f32x2 ls2 = {0.f, 0.f};
;           unsigned pw[2][4];
; #pragma unroll
;           for (int kb = 0; kb < 4; ++kb)
; #pragma unroll
;             for (int h = 0; h < 2; ++h) {
;               const f32x2 pe = {__builtin_amdgcn_exp2f(t[kb][h].x), __builtin_amdgcn_exp2f(t[kb][h].y)};
;               ls2 += pe;
;               pw[kb >> 1][(kb & 1) * 2 + h] = pk2(pe.x, pe.y);
;             }
;           l[qb] += ls2.x + ls2.y;
; #pragma unroll
;           for (int c = 0; c < 2; ++c) {
;             const u32x4 pv = (u32x4){pw[c][0], pw[c][1], pw[c][2], pw[c][3]};
;             pf[qb][c] = __builtin_bit_cast(bf16x8, pv);
;           }
;         }
;     ...
;   if (wact) {
; #pragma unroll
;     for (int qb = 0; qb < QB; ++qb) {
;       const float lt = xsum32(xsum16(l[qb]));
;       const float inv = 1.0f / lt;
;       const int qi = w * QB * 16 + qb * 16 + l16;
;       if (qi < a.nq) {
; #pragma unroll
;         for (int db = 0; db < 4; ++db) {
;           const f32x4 v = o[db][qb] * inv;
;           *(u32x2*)(a.O + blk_off(a.orow0 + qi, a.ocol0 + db * 16 + g * 4)) = (u32x2){pk2(v[0], v[1]), pk2(v[2], v[3])};
;         }
;       }
.LBB0_2305:
	s_or_b64 exec, exec, s[0:1]
	s_nop 0
	s_mov_b64 s[8:9], 0
	v_add_f32_e32 v18, v72, v68
	v_add_f32_e32 v19, v73, v69
	s_nop 0
	v_add_f32_e32 v18, v70, v18
	v_add_f32_e32 v19, v71, v19
	s_nop 0
	v_add_f32_e32 v18, v70, v18
	v_add_f32_e32 v19, v71, v19
	s_nop 0
	v_add_f32_e32 v18, v70, v18
	v_add_f32_e32 v19, v71, v19
	s_nop 0
	v_add_f32_e32 v18, v70, v18
	v_add_f32_e32 v19, v71, v19
	s_nop 0
	v_add_f32_e32 v18, v70, v18
	v_add_f32_e32 v19, v71, v19
	s_nop 0
	v_add_f32_e32 v18, v70, v18
	v_add_f32_e32 v19, v71, v19
	s_nop 0
	v_add_f32_e32 v18, v18, v19
	v_add_f32_e32 v18, v100, v18
	v_mov_b32_e32 v19, v18
	s_nop 1
	v_permlane16_swap_b32_e32 v18, v19
	v_add_f32_e32 v19, v18, v19
	v_mov_b32_e32 v20, v19
	v_or_b32_e32 v18, 16, v35
	s_nop 0
	v_permlane32_swap_b32_e32 v19, v20
	v_cmp_gt_i32_e32 vcc, s57, v18
	s_and_saveexec_b64 s[0:1], vcc
	s_xor_b64 s[0:1], exec, s[0:1]
	s_cbranch_execz .LBB0_2307
	v_add_f32_e32 v19, v19, v20
	v_div_scale_f32 v20, s[8:9], v19, v19, 1.0
	v_rcp_f32_e32 v21, v20
	s_lshl_b32 s3, s58, 1
	v_readlane_b32 s28, v251, 54
	v_readlane_b32 s29, v251, 55
	v_fma_f32 v22, -v20, v21, 1.0
	v_fmac_f32_e32 v21, v22, v21
	v_div_scale_f32 v22, vcc, 1.0, v19, 1.0
	v_mul_f32_e32 v23, v22, v21
	v_fma_f32 v24, -v20, v23, v22
	v_fmac_f32_e32 v23, v24, v21
	v_fma_f32 v20, -v20, v23, v22
	v_div_fmas_f32 v20, v20, v21, v23
	v_div_fixup_f32 v20, v20, v19, 1.0
	v_pk_mul_f32 v[16:17], v[16:17], v[20:21] op_sel_hi:[1,0]
	v_pk_mul_f32 v[14:15], v[14:15], v[20:21] op_sel_hi:[1,0]
	v_pk_mul_f32 v[8:9], v[8:9], v[20:21] op_sel_hi:[1,0]
	v_cvt_pk_bf16_f32 v14, v14, v15
	v_cvt_pk_bf16_f32 v15, v16, v17
	v_add_u32_e32 v16, s59, v18
	v_ashrrev_i32_e32 v17, 31, v16
	v_mad_u64_u32 v[18:19], s[8:9], s3, v206, v[16:17]
	v_pk_mul_f32 v[6:7], v[6:7], v[20:21] op_sel_hi:[1,0]
	s_or_b32 s3, s3, 1
	v_cvt_pk_bf16_f32 v6, v6, v7
	v_cvt_pk_bf16_f32 v7, v8, v9
	v_mad_u64_u32 v[8:9], s[8:9], s3, v206, v[16:17]
	v_lshlrev_b64 v[18:19], 6, v[18:19]
	v_lshlrev_b64 v[8:9], 6, v[8:9]
	v_lshl_add_u64 v[18:19], s[28:29], 0, v[18:19]
	v_lshl_add_u64 v[8:9], s[28:29], 0, v[8:9]
	v_or3_b32 v64, s56, v34, 48
	v_lshl_add_u64 v[18:19], v[18:19], 0, v[0:1]
	v_lshl_add_u64 v[8:9], v[8:9], 0, v[0:1]
	v_lshrrev_b32_e32 v0, 5, v64
	v_pk_mul_f32 v[12:13], v[12:13], v[20:21] op_sel_hi:[1,0]
	v_pk_mul_f32 v[10:11], v[10:11], v[20:21] op_sel_hi:[1,0]
	v_pk_mul_f32 v[4:5], v[4:5], v[20:21] op_sel_hi:[1,0]
	v_pk_mul_f32 v[2:3], v[2:3], v[20:21] op_sel_hi:[1,0]
	v_mad_u64_u32 v[62:63], s[8:9], v0, s93, v[16:17]
	v_cvt_pk_bf16_f32 v10, v10, v11
	v_cvt_pk_bf16_f32 v11, v12, v13
	v_cvt_pk_bf16_f32 v60, v2, v3
	v_cvt_pk_bf16_f32 v61, v4, v5
	s_mov_b64 s[8:9], exec
	global_store_dwordx2 v[18:19], v[14:15], off
	global_store_dwordx2 v[18:19], v[10:11], off offset:32
	global_store_dwordx2 v[8:9], v[6:7], off

; #define RAW_BARRIER() do { asm volatile("s_waitcnt lgkmcnt(0)" ::: "memory"); __builtin_amdgcn_s_barrier(); } while (0)
; template <int DK, int QB, bool NA>
; DEVI void attn_item(const AttnArgs& a, unsigned char* smem) {
;     ...
;   bf16x8 qf[QB][KS];
; #pragma unroll
;   for (int qb = 0; qb < QB; ++qb) {
;     const bf16_t* qp = a.Q + (size_t)((wact ? w * QB * 16 : 0) + qb * 16 + l16) * a.ldq + g * 8;
; #pragma unroll
;     for (int ks = 0; ks < KS; ++ks) qf[qb][ks] = *(const bf16x8*)(qp + ks * 32);
;   }
;   float m[QB], l[QB];
;   f32x4 o[4][QB];
; #pragma unroll
;   for (int qb = 0; qb < QB; ++qb) {
;     m[qb] = NA ? -1e30f : 0.f; l[qb] = 0.f;
; #pragma unroll
;     for (int db = 0; db < 4; ++db) o[db][qb] = (f32x4){0.f, 0.f, 0.f, 0.f};
;   }
;   const int r8 = tid >> 3, c8 = (tid & 7) ^ ((tid >> 4) & 7);
;   const bf16_t* Kn = a.K + (size_t)r8 * a.ldk + c8 * 8;
;   const bf16_t* Kr = a.K + (size_t)(tid >> 2) * a.ldk + 64 + (((tid & 3) ^ ((0 - (tid >> 4)) & 3)) * 8);
;   const bf16_t* Vg = a.Vt + (size_t)r8 * a.Lk + c8 * 8;
;   const size_t kstep = (size_t)32 * a.ldk, vstep = (size_t)32 * a.Lk;
;   unsigned char* lds_t = smem + tid * 16;
;     ...
;   asm volatile("s_waitcnt vmcnt(0)" ::: "memory");
;   RAW_BARRIER();
;   ATT_ISSUE(0, 0);
;   if (nt > 1) ATT_ISSUE(1, 1);
;   const int sw8 = (l16 >> 1) & 7, vsw = sw8 << 1;
;   const unsigned ka0 = l16 * 128 + ((g ^ sw8) << 4), ka1 = l16 * 128 + (((4 + g) ^ sw8) << 4);
;   const unsigned kr = 8192 + l16 * 64 + ((g ^ ((0 - (l16 >> 2)) & 3)) << 4);
;   const unsigned vb00 = 12288 + l16 * 128 + (((0 + g) ^ vsw) << 3), vb01 = 12288 + l16 * 128 + (((4 + g) ^ vsw) << 3);
;   const unsigned vb10 = 12288 + l16 * 128 + (((8 + g) ^ vsw) << 3), vb11 = 12288 + l16 * 128 + (((12 + g) ^ vsw) << 3);
;   const unsigned biasA = lbase + ATT_BIAS_OFF;
;   const int qc = w * 16 + l16;
;   const int cs0 = min(max(qc - 8, 0), 48);
;   int cs = 0, is = 2;
;   for (int j = 0; j < nt; ++j) {
;     if (j + 1 < nt) {
;       if constexpr (DK == 96) asm volatile("s_waitcnt vmcnt(5)" ::: "memory");
;       else                    asm volatile("s_waitcnt vmcnt(4)" ::: "memory");
;     } else {
;       asm volatile("s_waitcnt vmcnt(0)" ::: "memory");
;     }
;     RAW_BARRIER();
;     if (j + 2 < nt) ATT_ISSUE(j + 2, is);
.LBB0_2309:
	s_mul_i32 s1, s59, 0x600
	v_readlane_b32 s3, v251, 58
	s_mul_hi_i32 s0, s59, 0x600
	s_add_u32 s3, s3, s1
	v_readlane_b32 s1, v251, 59
	s_mul_i32 s20, s58, 0x60
	s_addc_u32 s9, s1, s0
	s_lshl_b64 s[0:1], s[20:21], 1
	s_add_u32 s8, s3, s0
	s_addc_u32 s9, s9, s1
	s_ashr_i32 s3, s2, 31
	s_mul_i32 s40, s2, 0x600
	v_readlane_b32 s28, v251, 60
	s_mul_hi_i32 s20, s2, 0x600
	s_add_u32 s40, s28, s40
	v_readlane_b32 s28, v251, 61
	s_addc_u32 s20, s28, s20
	s_add_u32 s40, s40, s0
	s_addc_u32 s41, s20, s1
	s_lshl_b64 s[0:1], s[2:3], 10
	v_readlane_b32 s2, v251, 62
	s_add_u32 s2, s2, s0
	v_readlane_b32 s0, v251, 63
	s_mul_i32 s20, s62, s56
	v_mov_b32_e32 v2, v177
	s_addc_u32 s3, s0, s1
	s_lshl_b64 s[0:1], s[20:21], 1
	s_add_u32 s2, s2, s0
	v_ashrrev_i32_e32 v0, 1, v2
	v_and_b32_e32 v208, 0xffffffe0, v0
	s_addc_u32 s3, s3, s1
	v_cmp_gt_i32_e64 s[0:1], s57, v208
	v_and_b32_e32 v186, 15, v2
	v_bfe_u32 v187, v2, 4, 2
	v_cndmask_b32_e64 v0, 0, v208, s[0:1]
	v_or_b32_e32 v3, v0, v186
	v_lshlrev_b32_e32 v0, 4, v187
	v_lshl_add_u64 v[4:5], s[8:9], 0, v[0:1]
	s_movk_i32 s20, 0x600
	v_or_b32_e32 v0, 16, v3
	v_ashrrev_i32_e32 v32, 4, v2
	v_mad_i64_i32 v[6:7], s[8:9], v3, s20, v[4:5]
	v_mad_i64_i32 v[4:5], s[8:9], v0, s20, v[4:5]
	v_xor_b32_e32 v0, v32, v2
	v_ashrrev_i32_e32 v3, 3, v2
	v_mov_b64_e32 v[28:29], s[40:41]
	v_lshlrev_b32_e32 v0, 4, v0
	v_mad_i64_i32 v[30:31], s[8:9], v3, s20, v[28:29]
	v_and_b32_e32 v0, 0x70, v0
	v_lshl_add_u64 v[114:115], v[30:31], 0, v[0:1]
	v_ashrrev_i32_e32 v30, 2, v2
	v_mad_i64_i32 v[28:29], s[8:9], v30, s20, v[28:29]
	v_sub_u32_e32 v30, 0, v32
	v_xor_b32_e32 v30, v2, v30
	v_lshlrev_b32_e32 v30, 4, v30
	v_and_b32_e32 v30, 48, v30
	v_mov_b32_e32 v31, v1
	v_lshl_add_u64 v[116:117], v[28:29], 0, v[30:31]
	v_mad_i64_i32 v[30:31], s[8:9], v3, s62, 0
	v_lshl_add_u64 v[30:31], v[30:31], 1, s[2:3]
	v_lshlrev_b32_e32 v216, 4, v2
	v_lshl_add_u64 v[112:113], v[30:31], 0, v[0:1]
	v_readfirstlane_b32 s2, v216
	v_add_u32_e32 v0, 0x1000, v216
	global_load_dwordx4 v[24:27], v[6:7], off
	global_load_dwordx4 v[16:19], v[6:7], off offset:64
	global_load_dwordx4 v[8:11], v[6:7], off offset:128
	global_load_dwordx4 v[20:23], v[4:5], off
	global_load_dwordx4 v[12:15], v[4:5], off offset:64
	s_nop 0
	global_load_dwordx4 v[4:7], v[4:5], off offset:128
	s_waitcnt vmcnt(0)
	s_mov_b32 m0, s2
	v_readfirstlane_b32 s2, v0
	v_add_u32_e32 v0, 0x2000, v216
	s_mov_b64 s[40:41], 0x80
	s_waitcnt lgkmcnt(0)
	s_barrier
	global_load_lds_dwordx4 v[114:115], off
	v_lshl_add_u64 v[30:31], v[114:115], 0, s[86:87]
	s_mov_b32 m0, s2
	v_readfirstlane_b32 s2, v0
	v_add_u32_e32 v0, 0x3000, v216
	v_lshl_add_u64 v[28:29], v[116:117], 0, s[40:41]
	global_load_lds_dwordx4 v[30:31], off
	s_mov_b32 m0, s2
	v_readfirstlane_b32 s2, v0
	v_add_u32_e32 v0, 0x4000, v216
	global_load_lds_dwordx4 v[28:29], off
	s_mov_b32 m0, s2
	s_lshl_b32 s20, s62, 6
	v_readfirstlane_b32 s2, v0
	v_add_u32_e32 v0, 0x5000, v216
	global_load_lds_dwordx4 v[112:113], off
	v_lshl_add_u64 v[118:119], v[112:113], 0, s[20:21]
	s_mov_b32 m0, s2
	v_readfirstlane_b32 s2, v0
	global_load_lds_dwordx4 v[118:119], off
	v_lshl_add_u64 v[28:29], v[114:115], 0, s[38:39]
	s_mov_b32 m0, s2
	s_mov_b64 s[2:3], 0x24000
	v_add_u32_e32 v0, 0x6000, v216
	global_load_lds_dwordx4 v[28:29], off
	v_lshl_add_u64 v[28:29], v[114:115], 0, s[2:3]
	v_readfirstlane_b32 s2, v0
	s_mov_b32 m0, s2
	s_mov_b64 s[2:3], 0x18080
	v_add_u32_e32 v0, 0x7000, v216
	global_load_lds_dwordx4 v[28:29], off
	v_lshl_add_u64 v[28:29], v[116:117], 0, s[2:3]
	v_readfirstlane_b32 s2, v0
	v_add_u32_e32 v0, 0x8000, v216
	s_mov_b32 m0, s2
	v_readfirstlane_b32 s2, v0
	v_add_u32_e32 v0, 0x9000, v216
	global_load_lds_dwordx4 v[28:29], off
	v_lshl_add_u64 v[28:29], v[112:113], 0, s[40:41]
	s_mov_b32 m0, s2
	v_readfirstlane_b32 s2, v0
	global_load_lds_dwordx4 v[28:29], off
	v_lshl_add_u64 v[28:29], v[118:119], 0, s[40:41]
	s_mov_b32 m0, s2
	v_add_u32_e32 v0, 0xa000, v216
	global_load_lds_dwordx4 v[28:29], off
	v_readfirstlane_b32 s2, v0
	s_waitcnt vmcnt(5)
	v_lshl_add_u64 v[28:29], v[114:115], 0, s[4:5]
	s_mov_b32 m0, s2
	s_mov_b64 s[2:3], 0x3c000
	v_add_u32_e32 v0, 0xb000, v216
	s_waitcnt lgkmcnt(0)
	s_barrier
	global_load_lds_dwordx4 v[28:29], off
	v_lshl_add_u64 v[28:29], v[114:115], 0, s[2:3]
	v_readfirstlane_b32 s2, v0
	s_mov_b32 m0, s2
	s_mov_b64 s[2:3], 0x30080
	v_add_u32_e32 v0, 0xc000, v216
	global_load_lds_dwordx4 v[28:29], off
	v_lshl_add_u64 v[28:29], v[116:117], 0, s[2:3]
	v_readfirstlane_b32 s2, v0
	v_add_u32_e32 v0, 0xd000, v216
	s_mov_b32 m0, s2
	s_mov_b64 s[8:9], 0x100
	v_readfirstlane_b32 s2, v0
	v_add_u32_e32 v0, 0xe000, v216
	global_load_lds_dwordx4 v[28:29], off
	v_lshl_add_u64 v[28:29], v[112:113], 0, s[8:9]
	s_mov_b32 m0, s2
	v_readfirstlane_b32 s2, v0
	global_load_lds_dwordx4 v[28:29], off
	v_lshl_add_u64 v[28:29], v[118:119], 0, s[8:9]
	s_mov_b32 m0, s2
	s_mov_b64 s[28:29], 0x80
	global_load_lds_dwordx4 v[28:29], off
	v_cmp_le_i32_e32 vcc, s57, v208
	s_and_saveexec_b64 s[2:3], vcc
	s_xor_b64 s[2:3], exec, s[2:3]
	s_or_saveexec_b64 s[2:3], s[2:3]
	v_lshrrev_b32_e32 v0, 4, v2
	v_bfe_u32 v3, v2, 1, 3
	v_lshrrev_b32_e32 v2, 2, v2
	v_lshlrev_b32_e32 v28, 1, v3
	v_lshlrev_b32_e32 v29, 7, v186
	v_bitop3_b32 v30, v0, v3, 3 bitop3:0x6c
	v_bitop3_b32 v3, v187, v3, 4 bitop3:0x36
	v_sub_u32_e32 v2, 0, v2
	v_lshl_or_b32 v213, v30, 4, v29
	v_lshl_or_b32 v214, v3, 4, v29
	v_or_b32_e32 v3, 0x3000, v29
	v_bitop3_b32 v29, v28, v0, 3 bitop3:0x78
	v_xor_b32_e32 v0, v0, v2
	v_lshl_or_b32 v209, v29, 3, v3
	v_bitop3_b32 v29, v187, v28, 4 bitop3:0x36
	v_lshlrev_b32_e32 v0, 4, v0
	v_lshl_or_b32 v210, v29, 3, v3
	v_bitop3_b32 v29, v187, v28, 8 bitop3:0x36
	v_bitop3_b32 v28, v187, v28, 12 bitop3:0x36
	v_and_b32_e32 v0, 48, v0
	v_lshlrev_b32_e32 v2, 6, v186
	s_movk_i32 s8, 0x2000
	v_lshl_or_b32 v211, v29, 3, v3
	v_lshl_or_b32 v212, v28, 3, v3
	v_or3_b32 v215, v0, v2, s8
	v_mov_b32_e32 v2, v1
	v_mov_b32_e32 v3, v1
	v_mov_b32_e32 v0, v1
	v_mov_b64_e32 v[30:31], v[2:3]
	v_mov_b64_e32 v[34:35], v[2:3]
	v_mov_b64_e32 v[38:39], v[2:3]
	v_mov_b64_e32 v[42:43], v[2:3]
	v_mov_b64_e32 v[46:47], v[2:3]
	v_mov_b64_e32 v[50:51], v[2:3]
	v_mov_b64_e32 v[54:55], v[2:3]
	v_mov_b64_e32 v[58:59], v[2:3]
	s_mov_b32 s9, 0
	v_mov_b32_e32 v108, 0
	v_mov_b64_e32 v[28:29], v[0:1]
	v_mov_b64_e32 v[32:33], v[0:1]
	v_mov_b64_e32 v[36:37], v[0:1]
	v_mov_b64_e32 v[40:41], v[0:1]
	v_mov_b64_e32 v[44:45], v[0:1]
	v_mov_b64_e32 v[48:49], v[0:1]
	v_mov_b64_e32 v[52:53], v[0:1]
	v_mov_b64_e32 v[56:57], v[0:1]
	v_mov_b32_e32 v109, 0
	v_mov_b32_e32 v110, 0
	v_mov_b32_e32 v111, 0
	s_xor_b64 exec, exec, s[2:3]
	s_cbranch_execz .LBB0_2311
	ds_read_b128 v[28:31], v213 offset:0
	ds_read_b128 v[32:35], v213 offset:0x800
	ds_read_b128 v[36:39], v213 offset:0x1000
	ds_read_b128 v[40:43], v213 offset:0x1800
	ds_read_b128 v[44:47], v214 offset:0
	ds_read_b128 v[48:51], v214 offset:0x800
	ds_read_b128 v[52:55], v214 offset:0x1000
	ds_read_b128 v[56:59], v214 offset:0x1800
	ds_read_b128 v[60:63], v215 offset:0
	ds_read_b128 v[64:67], v215 offset:0x400
	ds_read_b128 v[76:79], v215 offset:0x800
	ds_read_b128 v[80:83], v215 offset:0xc00
	s_nop 0
	s_waitcnt lgkmcnt(8)
	s_waitcnt vmcnt(0)
	s_setprio 1
	v_mfma_f32_16x16x32_bf16 v[68:71], v[28:31], v[24:27], 0
	s_waitcnt lgkmcnt(4)
	v_mfma_f32_16x16x32_bf16 v[28:31], v[28:31], v[20:23], 0
	v_mfma_f32_16x16x32_bf16 v[72:75], v[32:35], v[24:27], 0
	v_mfma_f32_16x16x32_bf16 v[32:35], v[32:35], v[20:23], 0
	v_mfma_f32_16x16x32_bf16 v[84:87], v[36:39], v[24:27], 0
	v_mfma_f32_16x16x32_bf16 v[36:39], v[36:39], v[20:23], 0
	v_mfma_f32_16x16x32_bf16 v[88:91], v[40:43], v[24:27], 0
	v_mfma_f32_16x16x32_bf16 v[40:43], v[40:43], v[20:23], 0
	v_mfma_f32_16x16x32_bf16 v[68:71], v[44:47], v[16:19], v[68:71]
	s_waitcnt lgkmcnt(0)
	v_mfma_f32_16x16x32_bf16 v[28:31], v[44:47], v[12:15], v[28:31]
	v_mfma_f32_16x16x32_bf16 v[44:47], v[48:51], v[16:19], v[72:75]
	v_mfma_f32_16x16x32_bf16 v[32:35], v[48:51], v[12:15], v[32:35]
	v_mfma_f32_16x16x32_bf16 v[48:51], v[52:55], v[16:19], v[84:87]
	v_mfma_f32_16x16x32_bf16 v[36:39], v[52:55], v[12:15], v[36:39]
	v_mfma_f32_16x16x32_bf16 v[52:55], v[56:59], v[16:19], v[88:91]
	v_mfma_f32_16x16x32_bf16 v[40:43], v[56:59], v[12:15], v[40:43]
	v_mfma_f32_16x16x32_bf16 v[84:87], v[60:63], v[8:11], v[68:71]
	ds_read_b64 v[56:57], v209 offset:0
	ds_read_b64 v[58:59], v210 offset:0
	v_mfma_f32_16x16x32_bf16 v[68:71], v[60:63], v[4:7], v[28:31]
	v_mfma_f32_16x16x32_bf16 v[60:63], v[64:67], v[8:11], v[44:47]
	s_nop 5
	v_mul_f32_e64 v92, v86, s34
	v_mul_f32_e64 v93, v87, s34
	v_pk_mul_f32 v[2:3], v[84:85], s[34:35] op_sel_hi:[1,0]
	v_max_f32_e32 v0, v92, v93
	v_mfma_f32_16x16x32_bf16 v[72:75], v[64:67], v[4:7], v[32:35]
	v_max3_f32 v0, v2, v3, v0
	v_pk_mul_f32 v[2:3], v[60:61], s[34:35] op_sel_hi:[1,0]
	v_mfma_f32_16x16x32_bf16 v[64:67], v[76:79], v[8:11], v[48:51]
	v_max_f32_e32 v92, v2, v3
	v_pk_mul_f32 v[2:3], v[62:63], s[34:35] op_sel_hi:[1,0]
	v_mfma_f32_16x16x32_bf16 v[88:91], v[80:83], v[8:11], v[52:55]
	v_max_f32_e32 v2, v2, v3
	v_max3_f32 v0, v0, v92, v2
	s_nop 2
	v_pk_mul_f32 v[2:3], v[64:65], s[34:35] op_sel_hi:[1,0]
	v_mfma_f32_16x16x32_bf16 v[76:79], v[76:79], v[4:7], v[36:39]
	v_max_f32_e32 v92, v2, v3
	v_pk_mul_f32 v[2:3], v[66:67], s[34:35] op_sel_hi:[1,0]
	ds_read_b64 v[52:53], v209 offset:0x800
	v_mfma_f32_16x16x32_bf16 v[80:83], v[80:83], v[4:7], v[40:43]
	s_setprio 0
	v_max_f32_e32 v2, v2, v3
	v_max3_f32 v0, v0, v92, v2
	v_pk_mul_f32 v[2:3], v[88:89], s[34:35] op_sel_hi:[1,0]
	ds_read_b64 v[54:55], v210 offset:0x800
	ds_read_b64 v[48:49], v209 offset:0x1000
	ds_read_b64 v[50:51], v210 offset:0x1000
	ds_read_b64 v[44:45], v209 offset:0x1800
	ds_read_b64 v[46:47], v210 offset:0x1800
	s_nop 0
	v_max_f32_e32 v92, v2, v3
	v_pk_mul_f32 v[2:3], v[90:91], s[34:35] op_sel_hi:[1,0]
	ds_read_b64 v[40:41], v211 offset:0
	ds_read_b64 v[42:43], v212 offset:0
	ds_read_b64 v[36:37], v211 offset:0x800
	ds_read_b64 v[38:39], v212 offset:0x800
	ds_read_b64 v[32:33], v211 offset:0x1000
	s_nop 0
	v_max_f32_e32 v2, v2, v3
	v_max3_f32 v0, v0, v92, v2
	v_mov_b32_e32 v2, v0
	s_nop 1
	v_permlane16_swap_b32_e32 v0, v2
	v_max_f32_e32 v2, v2, v2
	v_max_f32_e32 v0, v0, v0
	v_max_f32_e32 v0, v0, v2
	v_mov_b32_e32 v2, v0
	s_nop 1
	v_permlane32_swap_b32_e32 v0, v2
	v_max_f32_e32 v2, v2, v2
	v_max_f32_e32 v0, v0, v0
	v_max_f32_e32 v92, v0, v2
	v_fma_f32 v94, v62, s34, -v92
	v_fma_f32 v95, v63, s34, -v92
	v_fma_f32 v62, v60, s34, -v92
	v_fma_f32 v63, v61, s34, -v92
	v_fma_f32 v60, v84, s34, -v92
	v_fma_f32 v61, v85, s34, -v92
	v_fma_f32 v86, v86, s34, -v92
	v_fma_f32 v87, v87, s34, -v92
	v_exp_f32_e32 v60, v60
	v_exp_f32_e32 v61, v61
	v_exp_f32_e32 v86, v86
	v_exp_f32_e32 v87, v87
	v_exp_f32_e32 v62, v62
	v_add_f32_e32 v84, 0, v60
	v_exp_f32_e32 v63, v63
	v_fma_f32 v64, v64, s34, -v92
	v_fma_f32 v65, v65, s34, -v92
	v_cvt_pk_bf16_f32 v60, v60, v61
	v_add_f32_e32 v84, v86, v84
	v_add_f32_e32 v85, v87, v61
	v_cvt_pk_bf16_f32 v61, v86, v87
	v_exp_f32_e32 v86, v94
	v_exp_f32_e32 v87, v95
	v_fma_f32 v66, v66, s34, -v92
	v_fma_f32 v67, v67, s34, -v92
	v_exp_f32_e32 v64, v64
	v_exp_f32_e32 v65, v65
	v_exp_f32_e32 v66, v66
	v_exp_f32_e32 v67, v67
	v_add_f32_e32 v84, v62, v84
	v_add_f32_e32 v85, v63, v85
	v_fma_f32 v88, v88, s34, -v92
	v_fma_f32 v89, v89, s34, -v92
	v_add_f32_e32 v84, v86, v84
	v_add_f32_e32 v85, v87, v85
	v_fma_f32 v90, v90, s34, -v92
	v_fma_f32 v91, v91, s34, -v92
	v_add_f32_e32 v84, v64, v84
	v_add_f32_e32 v85, v65, v85
	v_cvt_pk_bf16_f32 v64, v64, v65
	v_add_f32_e32 v84, v66, v84
	v_add_f32_e32 v85, v67, v85
	v_cvt_pk_bf16_f32 v65, v66, v67
	v_exp_f32_e32 v66, v88
	v_exp_f32_e32 v67, v89
	v_cvt_pk_bf16_f32 v62, v62, v63
	v_cvt_pk_bf16_f32 v63, v86, v87
	v_exp_f32_e32 v86, v90
	v_exp_f32_e32 v87, v91
	v_add_f32_e32 v84, v66, v84
	v_add_f32_e32 v85, v67, v85
	v_pk_mul_f32 v[88:89], v[70:71], s[34:35] op_sel_hi:[1,0]
	v_cvt_pk_bf16_f32 v66, v66, v67
	v_add_f32_e32 v84, v86, v84
	v_add_f32_e32 v85, v87, v85
	v_cvt_pk_bf16_f32 v67, v86, v87
	v_pk_mul_f32 v[86:87], v[68:69], s[34:35] op_sel_hi:[1,0]
	v_max_f32_e32 v0, v88, v89
	v_max3_f32 v0, v86, v87, v0
	v_pk_mul_f32 v[86:87], v[72:73], s[34:35] op_sel_hi:[1,0]
	v_exp_f32_e64 v3, -v92
	v_max_f32_e32 v2, v86, v87
	v_pk_mul_f32 v[86:87], v[74:75], s[34:35] op_sel_hi:[1,0]
	ds_read_b64 v[34:35], v212 offset:0x1000
	ds_read_b64 v[28:29], v211 offset:0x1800
	ds_read_b64 v[30:31], v212 offset:0x1800
	s_nop 0
	v_max_f32_e32 v86, v86, v87
	v_max3_f32 v0, v0, v2, v86
	v_pk_mul_f32 v[86:87], v[76:77], s[34:35] op_sel_hi:[1,0]
	s_waitcnt lgkmcnt(0)
; template <int DK, int QB, bool NA>
; DEVI void attn_item(const AttnArgs& a, unsigned char* smem) {
;     ...
;           float mx = fmaxf(t[0][0].x, t[0][0].y);
; #pragma unroll
;           for (int kb = 0; kb < 4; ++kb)
; #pragma unroll
;             for (int h = 0; h < 2; ++h) mx = fmaxf(mx, fmaxf(t[kb][h].x, t[kb][h].y));
;           if (j == 0 || __any(mx > 6.f)) {
;             mx = xmax32(xmax16(mx));
;             const float d = (j == 0) ? mx : fmaxf(mx, 0.f);
;             const float alpha = __builtin_amdgcn_exp2f(-d);
;             const f32x2 dv = {d, d};
; #pragma unroll
;             for (int kb = 0; kb < 4; ++kb)
; #pragma unroll
;               for (int h = 0; h < 2; ++h) t[kb][h] -= dv;
;             m[qb] += d;
;             l[qb] *= alpha;
; #pragma unroll
;             for (int db = 0; db < 4; ++db) o[db][qb] *= alpha;
;           }
;           f32x2 ls2 = {0.f, 0.f};
;           unsigned pw[2][4];
; #pragma unroll
;           for (int kb = 0; kb < 4; ++kb)
; #pragma unroll
;             for (int h = 0; h < 2; ++h) {
;               const f32x2 pe = {__builtin_amdgcn_exp2f(t[kb][h].x), __builtin_amdgcn_exp2f(t[kb][h].y)};
;               ls2 += pe;
;               pw[kb >> 1][(kb & 1) * 2 + h] = pk2(pe.x, pe.y);
;             }
;           l[qb] += ls2.x + ls2.y;
; #pragma unroll
;           for (int c = 0; c < 2; ++c) {
;             const u32x4 pv = (u32x4){pw[c][0], pw[c][1], pw[c][2], pw[c][3]};
;             pf[qb][c] = __builtin_bit_cast(bf16x8, pv);
;           }
;         }
;     ...
;       asm volatile("s_waitcnt lgkmcnt(0)"
;                    : "+v"(va[0][0]), "+v"(va[0][1]), "+v"(va[0][2]), "+v"(va[0][3]), "+v"(va[1][0]), "+v"(va[1][1]), "+v"(va[1][2]), "+v"(va[1][3]),
;                      "+v"(vbq[0][0]), "+v"(vbq[0][1]), "+v"(vbq[0][2]), "+v"(vbq[0][3]), "+v"(vbq[1][0]), "+v"(vbq[1][1]), "+v"(vbq[1][2]), "+v"(vbq[1][3])
;                    :: "memory");
;       __builtin_amdgcn_sched_barrier(0);
; #pragma unroll
;       for (int c = 0; c < 2; ++c)
; #pragma unroll
;         for (int db = 0; db < 4; ++db) {
;           const u32x4 vw = (u32x4){va[c][db].x, va[c][db].y, vbq[c][db].x, vbq[c][db].y};
;           const bf16x8 vf = __builtin_bit_cast(bf16x8, vw);
; #pragma unroll
;           for (int qb = 0; qb < QB; ++qb) o[db][qb] = __builtin_amdgcn_mfma_f32_16x16x32_bf16(vf, pf[qb][c], o[db][qb], 0, 0, 0);
;         }
	s_nop 0
	v_max_f32_e32 v2, v86, v87
	v_pk_mul_f32 v[86:87], v[78:79], s[34:35] op_sel_hi:[1,0]
	s_nop 0
	v_max_f32_e32 v86, v86, v87
	v_max3_f32 v0, v0, v2, v86
	v_pk_mul_f32 v[86:87], v[80:81], s[34:35] op_sel_hi:[1,0]
	s_nop 0
	v_max_f32_e32 v2, v86, v87
	v_pk_mul_f32 v[86:87], v[82:83], s[34:35] op_sel_hi:[1,0]
	s_nop 0
	v_max_f32_e32 v86, v86, v87
	v_max3_f32 v0, v0, v2, v86
	v_mov_b32_e32 v2, v0
	s_nop 1
	v_permlane16_swap_b32_e32 v0, v2
	v_max_f32_e32 v2, v2, v2
	v_max_f32_e32 v0, v0, v0
	v_max_f32_e32 v0, v0, v2
	v_mov_b32_e32 v2, v0
	s_nop 1
	v_permlane32_swap_b32_e32 v0, v2
	v_max_f32_e32 v2, v2, v2
	v_max_f32_e32 v0, v0, v0
	v_max_f32_e32 v93, v0, v2
	v_mov_b32_e32 v0, v93
	v_fma_f32 v68, v68, s34, -v0
	v_fma_f32 v69, v69, s34, -v0
	v_fma_f32 v70, v70, s34, -v0
	v_fma_f32 v71, v71, s34, -v0
	v_exp_f32_e32 v68, v68
	v_exp_f32_e32 v69, v69
	v_exp_f32_e32 v70, v70
	v_exp_f32_e32 v71, v71
	v_fma_f32 v72, v72, s34, -v0
	v_fma_f32 v73, v73, s34, -v0
	v_add_f32_e32 v86, 0, v68
	v_add_f32_e32 v87, 0, v69
	v_fma_f32 v74, v74, s34, -v0
	v_fma_f32 v75, v75, s34, -v0
	v_cvt_pk_bf16_f32 v68, v68, v69
	v_add_f32_e32 v86, v70, v86
	v_add_f32_e32 v87, v71, v87
	v_cvt_pk_bf16_f32 v69, v70, v71
	v_exp_f32_e32 v70, v72
	v_exp_f32_e32 v71, v73
	v_exp_f32_e32 v74, v74
	v_exp_f32_e32 v75, v75
	v_fma_f32 v76, v76, s34, -v0
	v_fma_f32 v77, v77, s34, -v0
	v_add_f32_e32 v72, v70, v86
	v_add_f32_e32 v73, v71, v87
	v_cvt_pk_bf16_f32 v70, v70, v71
	v_add_f32_e32 v72, v74, v72
	v_add_f32_e32 v73, v75, v73
	v_cvt_pk_bf16_f32 v71, v74, v75
	v_exp_f32_e32 v74, v76
	v_exp_f32_e32 v75, v77
	v_fma_f32 v78, v78, s34, -v0
	v_fma_f32 v79, v79, s34, -v0
	v_fma_f32 v80, v80, s34, -v0
	v_fma_f32 v81, v81, s34, -v0
	v_fma_f32 v82, v82, s34, -v0
	v_fma_f32 v83, v83, s34, -v0
	v_add_f32_e32 v76, v74, v72
	v_add_f32_e32 v77, v75, v73
	v_cvt_pk_bf16_f32 v72, v74, v75
	v_exp_f32_e32 v74, v78
	v_exp_f32_e32 v75, v79
	v_exp_f32_e32 v78, v82
	v_exp_f32_e32 v79, v83
	v_exp_f32_e64 v2, -v93
	v_add_f32_e32 v76, v74, v76
	v_add_f32_e32 v77, v75, v77
	v_cvt_pk_bf16_f32 v73, v74, v75
	v_exp_f32_e32 v74, v80
	v_exp_f32_e32 v75, v81
	v_add_f32_e32 v110, 0, v92
	v_add_f32_e32 v111, 0, v93
	v_add_f32_e32 v76, v74, v76
	v_add_f32_e32 v77, v75, v77
	s_nop 0
	v_add_f32_e32 v86, v78, v76
	v_add_f32_e32 v87, v79, v77
	v_cvt_pk_bf16_f32 v74, v74, v75
	v_cvt_pk_bf16_f32 v75, v78, v79
	v_mov_b32_e32 v78, v86
	v_mov_b32_e32 v79, v84
	v_mov_b32_e32 v84, v87
	v_add_f32_e32 v84, v78, v84
	v_add_f32_e32 v85, v79, v85
	v_pk_mul_f32 v[76:77], v[2:3], 0 op_sel_hi:[1,0]
	v_pk_fma_f32 v[108:109], v[2:3], 0, v[84:85] op_sel_hi:[1,0,1]
	v_mov_b32_e32 v80, v77
	v_mov_b32_e32 v81, v77
	v_mov_b32_e32 v82, v77
	v_mov_b32_e32 v83, v77
	v_mov_b32_e32 v77, v76
	v_mov_b32_e32 v78, v76
	v_mov_b32_e32 v79, v76
	s_setprio 1
	v_mfma_f32_16x16x32_bf16 v[84:87], v[56:59], v[60:63], v[80:83]
	s_nop 0
	v_mfma_f32_16x16x32_bf16 v[88:91], v[56:59], v[68:71], v[76:79]
	v_mfma_f32_16x16x32_bf16 v[92:95], v[52:55], v[60:63], v[80:83]
	v_mfma_f32_16x16x32_bf16 v[96:99], v[52:55], v[68:71], v[76:79]
	v_mfma_f32_16x16x32_bf16 v[100:103], v[48:51], v[60:63], v[80:83]
	v_mfma_f32_16x16x32_bf16 v[104:107], v[48:51], v[68:71], v[76:79]
	v_mfma_f32_16x16x32_bf16 v[60:63], v[44:47], v[60:63], v[80:83]
	v_mfma_f32_16x16x32_bf16 v[68:71], v[44:47], v[68:71], v[76:79]
	v_mfma_f32_16x16x32_bf16 v[56:59], v[40:43], v[64:67], v[84:87]
	v_mfma_f32_16x16x32_bf16 v[52:55], v[40:43], v[72:75], v[88:91]
	v_mfma_f32_16x16x32_bf16 v[48:51], v[36:39], v[64:67], v[92:95]
	v_mfma_f32_16x16x32_bf16 v[44:47], v[36:39], v[72:75], v[96:99]
	v_mfma_f32_16x16x32_bf16 v[40:43], v[32:35], v[64:67], v[100:103]
	v_mfma_f32_16x16x32_bf16 v[36:39], v[32:35], v[72:75], v[104:107]
	v_mfma_f32_16x16x32_bf16 v[32:35], v[28:31], v[64:67], v[60:63]
	v_mfma_f32_16x16x32_bf16 v[28:31], v[28:31], v[72:75], v[68:71]
	s_setprio 0
; DEVI unsigned pk2(float lo, float hi) { const f32x2_t v = {lo, hi}; const bf16x2_t b = __builtin_convertvector(v, bf16x2_t); return __builtin_bit_cast(unsigned, b); }
; template <int DK, int QB, bool NA>
; DEVI void attn_item(const AttnArgs& a, unsigned char* smem) {
;     ...
;           f32x2 ls2 = {0.f, 0.f};
;           unsigned pw[2][4];
; #pragma unroll
;           for (int kb = 0; kb < 4; ++kb)
; #pragma unroll
;             for (int h = 0; h < 2; ++h) {
;               const f32x2 pe = {__builtin_amdgcn_exp2f(t[kb][h].x), __builtin_amdgcn_exp2f(t[kb][h].y)};
;               ls2 += pe;
;               pw[kb >> 1][(kb & 1) * 2 + h] = pk2(pe.x, pe.y);
;             }
;           l[qb] += ls2.x + ls2.y;
; #pragma unroll
;           for (int c = 0; c < 2; ++c) {
;             const u32x4 pv = (u32x4){pw[c][0], pw[c][1], pw[c][2], pw[c][3]};
;             pf[qb][c] = __builtin_bit_cast(bf16x8, pv);
;           }
;         }
;     ...
;       asm volatile("s_waitcnt lgkmcnt(0)"
;                    : "+v"(va[0][0]), "+v"(va[0][1]), "+v"(va[0][2]), "+v"(va[0][3]), "+v"(va[1][0]), "+v"(va[1][1]), "+v"(va[1][2]), "+v"(va[1][3]),
;                      "+v"(vbq[0][0]), "+v"(vbq[0][1]), "+v"(vbq[0][2]), "+v"(vbq[0][3]), "+v"(vbq[1][0]), "+v"(vbq[1][1]), "+v"(vbq[1][2]), "+v"(vbq[1][3])
;                    :: "memory");
;       __builtin_amdgcn_sched_barrier(0);
; #pragma unroll
;       for (int c = 0; c < 2; ++c)
; #pragma unroll
;         for (int db = 0; db < 4; ++db) {
;           const u32x4 vw = (u32x4){va[c][db].x, va[c][db].y, vbq[c][db].x, vbq[c][db].y};
;           const bf16x8 vf = __builtin_bit_cast(bf16x8, vw);
; #pragma unroll
;           for (int qb = 0; qb < QB; ++qb) o[db][qb] = __builtin_amdgcn_mfma_f32_16x16x32_bf16(vf, pf[qb][c], o[db][qb], 0, 0, 0);
;         }
.LBB0_2311:
	s_or_b64 exec, exec, s[2:3]
	s_mov_b32 s8, 1
	s_mov_b32 s42, 2
	s_movk_i32 s43, 0xc0
	s_waitcnt vmcnt(0)
	s_branch .LBB0_2314
	.p2align	6
	s_nop 0
	s_nop 0
	s_nop 0
	s_nop 0
.LBB0_2312:
	v_exp_f32_e32 v94, v182
	v_exp_f32_e32 v95, v183
	v_exp_f32_e32 v182, v180
	v_exp_f32_e32 v183, v181
	v_exp_f32_e32 v126, v126
	v_exp_f32_e32 v127, v127
	v_exp_f32_e32 v128, v128
	v_exp_f32_e32 v129, v129
	v_cvt_pk_bf16_f32 v180, v94, v95
	v_add_f32_e32 v94, v182, v94
	v_add_f32_e32 v95, v183, v95
	v_exp_f32_e32 v124, v124
	v_exp_f32_e32 v125, v125
	v_cvt_pk_bf16_f32 v181, v182, v183
	v_add_f32_e32 v94, v126, v94
	v_add_f32_e32 v95, v127, v95
	v_cvt_pk_bf16_f32 v182, v126, v127
	v_exp_f32_e32 v126, v122
	v_exp_f32_e32 v127, v123
	v_exp_f32_e32 v120, v120
	v_exp_f32_e32 v121, v121
	v_add_f32_e32 v94, v128, v94
	v_add_f32_e32 v95, v129, v95
	v_exp_f32_e32 v2, v2
	v_exp_f32_e32 v3, v3
	v_add_f32_e32 v94, v124, v94
	v_add_f32_e32 v95, v125, v95
	v_cvt_pk_bf16_f32 v122, v124, v125
	v_add_f32_e32 v94, v126, v94
	v_add_f32_e32 v95, v127, v95
	v_cvt_pk_bf16_f32 v125, v2, v3
	v_add_f32_e32 v94, v120, v94
	v_add_f32_e32 v95, v121, v95
	v_exp_f32_e32 v104, v104
	v_add_f32_e32 v94, v2, v94
	v_add_f32_e32 v95, v3, v95
	v_exp_f32_e32 v2, v184
	v_exp_f32_e32 v3, v185
	v_add_f32_e32 v0, v94, v95
	v_exp_f32_e32 v94, v106
	v_exp_f32_e32 v95, v107
	v_exp_f32_e32 v105, v105
	v_exp_f32_e32 v102, v102
	v_exp_f32_e32 v103, v103
	v_cvt_pk_bf16_f32 v123, v126, v127
	v_cvt_pk_bf16_f32 v126, v2, v3
	v_add_f32_e32 v2, v94, v2
	v_add_f32_e32 v3, v95, v3
	v_cvt_pk_bf16_f32 v127, v94, v95
	v_exp_f32_e32 v94, v100
	v_exp_f32_e32 v95, v101
	v_exp_f32_e32 v98, v98
	v_exp_f32_e32 v99, v99
	v_add_f32_e32 v2, v104, v2
	v_add_f32_e32 v3, v105, v3
	v_exp_f32_e32 v96, v96
	v_exp_f32_e32 v97, v97
	v_add_f32_e32 v2, v102, v2
	v_add_f32_e32 v3, v103, v3
	v_exp_f32_e32 v92, v92
	v_exp_f32_e32 v93, v93
	v_add_f32_e32 v2, v94, v2
	v_add_f32_e32 v3, v95, v3
	s_waitcnt lgkmcnt(0)
	v_add_f32_e32 v109, v109, v0
	v_add_f32_e32 v2, v98, v2
	v_add_f32_e32 v3, v99, v3
	v_cvt_pk_bf16_f32 v183, v128, v129
	v_add_f32_e32 v2, v96, v2
	v_add_f32_e32 v3, v97, v3
	v_cvt_pk_bf16_f32 v124, v120, v121
	v_add_f32_e32 v2, v92, v2
	v_add_f32_e32 v3, v93, v3
	v_cvt_pk_bf16_f32 v128, v104, v105
	v_add_f32_e32 v0, v2, v3
	v_add_f32_e32 v108, v108, v0
	v_cvt_pk_bf16_f32 v129, v102, v103
	v_cvt_pk_bf16_f32 v94, v94, v95
	v_cvt_pk_bf16_f32 v95, v98, v99
	v_cvt_pk_bf16_f32 v96, v96, v97
	v_cvt_pk_bf16_f32 v97, v92, v93
	s_setprio 1
	v_mfma_f32_16x16x32_bf16 v[56:59], v[88:91], v[180:183], v[56:59]
	v_mfma_f32_16x16x32_bf16 v[52:55], v[88:91], v[126:129], v[52:55]
	v_mfma_f32_16x16x32_bf16 v[48:51], v[84:87], v[180:183], v[48:51]
	v_mfma_f32_16x16x32_bf16 v[44:47], v[84:87], v[126:129], v[44:47]
	v_mfma_f32_16x16x32_bf16 v[40:43], v[80:83], v[180:183], v[40:43]
	v_mfma_f32_16x16x32_bf16 v[36:39], v[80:83], v[126:129], v[36:39]
	v_mfma_f32_16x16x32_bf16 v[32:35], v[76:79], v[180:183], v[32:35]
	v_mfma_f32_16x16x32_bf16 v[28:31], v[76:79], v[126:129], v[28:31]
	v_mfma_f32_16x16x32_bf16 v[56:59], v[72:75], v[122:125], v[56:59]
	v_mfma_f32_16x16x32_bf16 v[52:55], v[72:75], v[94:97], v[52:55]
	v_mfma_f32_16x16x32_bf16 v[48:51], v[68:71], v[122:125], v[48:51]
	v_mfma_f32_16x16x32_bf16 v[44:47], v[68:71], v[94:97], v[44:47]
	v_mfma_f32_16x16x32_bf16 v[40:43], v[64:67], v[122:125], v[40:43]
	v_mfma_f32_16x16x32_bf16 v[36:39], v[64:67], v[94:97], v[36:39]
	v_mfma_f32_16x16x32_bf16 v[32:35], v[60:63], v[122:125], v[32:35]
	v_mfma_f32_16x16x32_bf16 v[28:31], v[60:63], v[94:97], v[28:31]
	s_setprio 0

; DEVI unsigned pk2(float lo, float hi) { const f32x2_t v = {lo, hi}; const bf16x2_t b = __builtin_convertvector(v, bf16x2_t); return __builtin_bit_cast(unsigned, b); }
; template <int DK, int QB, bool NA>
; DEVI void attn_item(const AttnArgs& a, unsigned char* smem) {
;     ...
;           f32x2 ls2 = {0.f, 0.f};
;           unsigned pw[2][4];
; #pragma unroll
;           for (int kb = 0; kb < 4; ++kb)
; #pragma unroll
;             for (int h = 0; h < 2; ++h) {
;               const f32x2 pe = {__builtin_amdgcn_exp2f(t[kb][h].x), __builtin_amdgcn_exp2f(t[kb][h].y)};
;               ls2 += pe;
;               pw[kb >> 1][(kb & 1) * 2 + h] = pk2(pe.x, pe.y);
;             }
;           l[qb] += ls2.x + ls2.y;
; #pragma unroll
;           for (int c = 0; c < 2; ++c) {
;             const u32x4 pv = (u32x4){pw[c][0], pw[c][1], pw[c][2], pw[c][3]};
;             pf[qb][c] = __builtin_bit_cast(bf16x8, pv);
;           }
;         }
;     ...
;       asm volatile("s_waitcnt lgkmcnt(0)"
;                    : "+v"(va[0][0]), "+v"(va[0][1]), "+v"(va[0][2]), "+v"(va[0][3]), "+v"(va[1][0]), "+v"(va[1][1]), "+v"(va[1][2]), "+v"(va[1][3]),
;                      "+v"(vbq[0][0]), "+v"(vbq[0][1]), "+v"(vbq[0][2]), "+v"(vbq[0][3]), "+v"(vbq[1][0]), "+v"(vbq[1][1]), "+v"(vbq[1][2]), "+v"(vbq[1][3])
;                    :: "memory");
;       __builtin_amdgcn_sched_barrier(0);
; #pragma unroll
;       for (int c = 0; c < 2; ++c)
; #pragma unroll
;         for (int db = 0; db < 4; ++db) {
;           const u32x4 vw = (u32x4){va[c][db].x, va[c][db].y, vbq[c][db].x, vbq[c][db].y};
;           const bf16x8 vf = __builtin_bit_cast(bf16x8, vw);
; #pragma unroll
;           for (int qb = 0; qb < QB; ++qb) o[db][qb] = __builtin_amdgcn_mfma_f32_16x16x32_bf16(vf, pf[qb][c], o[db][qb], 0, 0, 0);
;         }
.LBB0_2326:
	v_exp_f32_e32 v94, v124
	v_exp_f32_e32 v95, v125
	v_exp_f32_e32 v124, v122
	v_exp_f32_e32 v125, v123
	v_exp_f32_e32 v118, v118
	v_exp_f32_e32 v119, v119
	v_exp_f32_e32 v120, v120
	v_exp_f32_e32 v121, v121
	v_cvt_pk_bf16_f32 v122, v94, v95
	v_add_f32_e32 v94, v124, v94
	v_add_f32_e32 v95, v125, v95
	v_exp_f32_e32 v116, v116
	v_exp_f32_e32 v117, v117
	v_cvt_pk_bf16_f32 v123, v124, v125
	v_add_f32_e32 v94, v118, v94
	v_add_f32_e32 v95, v119, v95
	v_cvt_pk_bf16_f32 v124, v118, v119
	v_exp_f32_e32 v118, v114
	v_exp_f32_e32 v119, v115
	v_exp_f32_e32 v112, v112
	v_exp_f32_e32 v113, v113
	v_add_f32_e32 v94, v120, v94
	v_add_f32_e32 v95, v121, v95
	v_exp_f32_e32 v2, v2
	v_exp_f32_e32 v3, v3
	v_add_f32_e32 v94, v116, v94
	v_add_f32_e32 v95, v117, v95
	v_cvt_pk_bf16_f32 v114, v116, v117
	v_add_f32_e32 v94, v118, v94
	v_add_f32_e32 v95, v119, v95
	v_cvt_pk_bf16_f32 v117, v2, v3
	v_add_f32_e32 v94, v112, v94
	v_add_f32_e32 v95, v113, v95
	v_exp_f32_e32 v104, v104
	v_add_f32_e32 v94, v2, v94
	v_add_f32_e32 v95, v3, v95
	v_exp_f32_e32 v2, v126
	v_exp_f32_e32 v3, v127
	v_add_f32_e32 v0, v94, v95
	v_exp_f32_e32 v94, v106
	v_exp_f32_e32 v95, v107
	v_exp_f32_e32 v105, v105
	v_exp_f32_e32 v102, v102
	v_exp_f32_e32 v103, v103
	v_cvt_pk_bf16_f32 v115, v118, v119
	v_cvt_pk_bf16_f32 v118, v2, v3
	v_add_f32_e32 v2, v94, v2
	v_add_f32_e32 v3, v95, v3
	v_cvt_pk_bf16_f32 v119, v94, v95
	v_exp_f32_e32 v94, v100
	v_exp_f32_e32 v95, v101
	v_exp_f32_e32 v98, v98
	v_exp_f32_e32 v99, v99
	v_add_f32_e32 v2, v104, v2
	v_add_f32_e32 v3, v105, v3
	v_exp_f32_e32 v96, v96
	v_exp_f32_e32 v97, v97
	v_add_f32_e32 v2, v102, v2
	v_add_f32_e32 v3, v103, v3
	v_exp_f32_e32 v92, v92
	v_exp_f32_e32 v93, v93
	v_add_f32_e32 v2, v94, v2
	v_add_f32_e32 v3, v95, v3
	s_waitcnt lgkmcnt(0)
	v_add_f32_e32 v109, v109, v0
	v_add_f32_e32 v2, v98, v2
	v_add_f32_e32 v3, v99, v3
	v_cvt_pk_bf16_f32 v125, v120, v121
	v_add_f32_e32 v2, v96, v2
	v_add_f32_e32 v3, v97, v3
	v_cvt_pk_bf16_f32 v116, v112, v113
	v_add_f32_e32 v2, v92, v2
	v_add_f32_e32 v3, v93, v3
	v_cvt_pk_bf16_f32 v120, v104, v105
	v_add_f32_e32 v0, v2, v3
	v_add_f32_e32 v108, v108, v0
	v_cvt_pk_bf16_f32 v121, v102, v103
	v_cvt_pk_bf16_f32 v94, v94, v95
	v_cvt_pk_bf16_f32 v95, v98, v99
	v_cvt_pk_bf16_f32 v96, v96, v97
	v_cvt_pk_bf16_f32 v97, v92, v93
	s_setprio 1
	v_mfma_f32_16x16x32_bf16 v[56:59], v[88:91], v[122:125], v[56:59]
	v_mfma_f32_16x16x32_bf16 v[52:55], v[88:91], v[118:121], v[52:55]
	v_mfma_f32_16x16x32_bf16 v[48:51], v[84:87], v[122:125], v[48:51]
	v_mfma_f32_16x16x32_bf16 v[44:47], v[84:87], v[118:121], v[44:47]
	v_mfma_f32_16x16x32_bf16 v[40:43], v[80:83], v[122:125], v[40:43]
	v_mfma_f32_16x16x32_bf16 v[36:39], v[80:83], v[118:121], v[36:39]
	v_mfma_f32_16x16x32_bf16 v[32:35], v[76:79], v[122:125], v[32:35]
	v_mfma_f32_16x16x32_bf16 v[28:31], v[76:79], v[118:121], v[28:31]
	v_mfma_f32_16x16x32_bf16 v[56:59], v[72:75], v[114:117], v[56:59]
	v_mfma_f32_16x16x32_bf16 v[52:55], v[72:75], v[94:97], v[52:55]
	v_mfma_f32_16x16x32_bf16 v[48:51], v[68:71], v[114:117], v[48:51]
	v_mfma_f32_16x16x32_bf16 v[44:47], v[68:71], v[94:97], v[44:47]
	v_mfma_f32_16x16x32_bf16 v[40:43], v[64:67], v[114:117], v[40:43]
	v_mfma_f32_16x16x32_bf16 v[36:39], v[64:67], v[94:97], v[36:39]
	v_mfma_f32_16x16x32_bf16 v[32:35], v[60:63], v[114:117], v[32:35]
	v_mfma_f32_16x16x32_bf16 v[28:31], v[60:63], v[94:97], v[28:31]
	s_setprio 0

; template <int DK, int QB, bool NA>
; DEVI void attn_item(const AttnArgs& a, unsigned char* smem) {
;     ...
;       const bool ismeta = (j == nt - 1);
;       bf16x8 pf[QB][2];
;       if constexpr (!NA) {
;         typedef float f32x2 __attribute__((ext_vector_type(2)));
; #pragma unroll
;         for (int qb = 0; qb < QB; ++qb) {
;           if (ismeta) {
; #pragma unroll
;             for (int kb = 1; kb < 4; ++kb) s[kb][qb] = (f32x4){-1e30f, -1e30f, -1e30f, -1e30f};
;           }
;           const f32x2 scv = {a.sc2, a.sc2}, nmv = {-m[qb], -m[qb]};
;           f32x2 t[4][2];
; #pragma unroll
;           for (int kb = 0; kb < 4; ++kb)
; #pragma unroll
;             for (int h = 0; h < 2; ++h) {
;               const f32x2 sv = {s[kb][qb][2 * h], s[kb][qb][2 * h + 1]};
;               t[kb][h] = sv * scv + nmv;
;             }
;           float mx = fmaxf(t[0][0].x, t[0][0].y);
; #pragma unroll
;           for (int kb = 0; kb < 4; ++kb)
; #pragma unroll
;             for (int h = 0; h < 2; ++h) mx = fmaxf(mx, fmaxf(t[kb][h].x, t[kb][h].y));
;           if (j == 0 || __any(mx > 6.f)) {
;             mx = xmax32(xmax16(mx));
;             const float d = (j == 0) ? mx : fmaxf(mx, 0.f);
;             const float alpha = __builtin_amdgcn_exp2f(-d);
;             const f32x2 dv = {d, d};
; #pragma unroll
;             for (int kb = 0; kb < 4; ++kb)
; #pragma unroll
;               for (int h = 0; h < 2; ++h) t[kb][h] -= dv;
;             m[qb] += d;
;             l[qb] *= alpha;
; #pragma unroll
;             for (int db = 0; db < 4; ++db) o[db][qb] *= alpha;
;           }
;           f32x2 ls2 = {0.f, 0.f};
;           unsigned pw[2][4];
; #pragma unroll
;           for (int kb = 0; kb < 4; ++kb)
; #pragma unroll
;             for (int h = 0; h < 2; ++h) {
;               const f32x2 pe = {__builtin_amdgcn_exp2f(t[kb][h].x), __builtin_amdgcn_exp2f(t[kb][h].y)};
;               ls2 += pe;
;               pw[kb >> 1][(kb & 1) * 2 + h] = pk2(pe.x, pe.y);
;             }
;           l[qb] += ls2.x + ls2.y;
; #pragma unroll
;           for (int c = 0; c < 2; ++c) {
;             const u32x4 pv = (u32x4){pw[c][0], pw[c][1], pw[c][2], pw[c][3]};
;             pf[qb][c] = __builtin_bit_cast(bf16x8, pv);
;           }
;         }
;     ...
;   if (wact) {
; #pragma unroll
;     for (int qb = 0; qb < QB; ++qb) {
;       const float lt = xsum32(xsum16(l[qb]));
.LBB0_2332:
	v_exp_f32_e32 v74, v74
	v_exp_f32_e32 v75, v75
	v_exp_f32_e32 v72, v72
	v_exp_f32_e32 v73, v73
	v_exp_f32_e32 v26, v26
	v_exp_f32_e32 v27, v27
	v_cvt_pk_bf16_f32 v78, v74, v75
	v_add_f32_e32 v74, v72, v74
	v_add_f32_e32 v75, v73, v75
	v_cvt_pk_bf16_f32 v79, v72, v73
	v_add_f32_e32 v72, v26, v74
	v_add_f32_e32 v73, v27, v75
	v_exp_f32_e32 v70, v70
	v_add_f32_e32 v72, v26, v72
	v_add_f32_e32 v73, v27, v73
	v_exp_f32_e32 v71, v71
	v_add_f32_e32 v72, v26, v72
	v_add_f32_e32 v73, v27, v73
	v_cvt_pk_bf16_f32 v80, v26, v27
	v_add_f32_e32 v72, v26, v72
	v_add_f32_e32 v73, v27, v73
	v_exp_f32_e32 v68, v68
	v_add_f32_e32 v72, v26, v72
	v_add_f32_e32 v73, v27, v73
	v_exp_f32_e32 v69, v69
	v_add_f32_e32 v26, v26, v72
	v_add_f32_e32 v27, v27, v73
	v_exp_f32_e32 v72, v76
	v_exp_f32_e32 v73, v77
	s_waitcnt lgkmcnt(0)
	v_add_f32_e32 v0, v26, v27
	v_add_f32_e32 v0, v109, v0
	v_cvt_pk_bf16_f32 v76, v70, v71
	v_mov_b32_e32 v81, v80
	v_mov_b32_e32 v82, v80
	v_mov_b32_e32 v83, v80
	v_mov_b32_e32 v84, v80
	v_mov_b32_e32 v85, v80
	v_cvt_pk_bf16_f32 v74, v68, v69
	v_cvt_pk_bf16_f32 v75, v72, v73
	v_mov_b32_e32 v77, v76
	v_mov_b32_e32 v86, v76
	v_mov_b32_e32 v87, v76
	v_mov_b32_e32 v88, v76
	v_mov_b32_e32 v89, v76
	s_setprio 1
	v_mfma_f32_16x16x32_bf16 v[56:59], v[64:67], v[78:81], v[56:59]
	s_mul_i32 s20, s58, 0x18500
	v_mfma_f32_16x16x32_bf16 v[52:55], v[64:67], v[74:77], v[52:55]
	v_mfma_f32_16x16x32_bf16 v[48:51], v[60:63], v[78:81], v[48:51]
	v_mfma_f32_16x16x32_bf16 v[44:47], v[60:63], v[74:77], v[44:47]
	v_mfma_f32_16x16x32_bf16 v[40:43], v[22:25], v[78:81], v[40:43]
	v_mfma_f32_16x16x32_bf16 v[22:25], v[22:25], v[74:77], v[36:39]
	v_mfma_f32_16x16x32_bf16 v[60:63], v[18:21], v[78:81], v[32:35]
	s_nop 1
	v_mov_b32_e32 v36, v0
	s_nop 1
	v_permlane16_swap_b32_e32 v0, v36
	v_mfma_f32_16x16x32_bf16 v[64:67], v[18:21], v[74:77], v[28:31]
	v_add_f32_e32 v36, v0, v36
	v_or_b32_e32 v35, v208, v186
	v_lshlrev_b32_e32 v34, 2, v187
	v_mfma_f32_16x16x32_bf16 v[30:33], v[14:17], v[82:85], v[56:59]
	v_mov_b32_e32 v37, v36
	s_nop 1
	v_permlane32_swap_b32_e32 v36, v37
	v_mfma_f32_16x16x32_bf16 v[14:17], v[14:17], v[86:89], v[52:55]
	v_cmp_gt_i32_e32 vcc, s57, v35
	v_lshlrev_b32_e32 v0, 1, v34
	v_mfma_f32_16x16x32_bf16 v[26:29], v[10:13], v[82:85], v[48:51]
	v_mfma_f32_16x16x32_bf16 v[10:13], v[10:13], v[86:89], v[44:47]
	v_mfma_f32_16x16x32_bf16 v[18:21], v[6:9], v[82:85], v[40:43]
	v_mfma_f32_16x16x32_bf16 v[6:9], v[6:9], v[86:89], v[22:25]
	v_mfma_f32_16x16x32_bf16 v[22:25], v[2:5], v[82:85], v[60:63]
	v_mfma_f32_16x16x32_bf16 v[2:5], v[2:5], v[86:89], v[64:67]
	s_setprio 0
	s_and_saveexec_b64 s[0:1], vcc
	s_cbranch_execz .LBB0_2334
	v_add_f32_e32 v36, v36, v37
	v_div_scale_f32 v37, s[8:9], v36, v36, 1.0
	v_rcp_f32_e32 v38, v37
	v_div_scale_f32 v39, vcc, 1.0, v36, 1.0
	s_add_i32 s8, s20, 0xc280
	v_fma_f32 v40, -v37, v38, 1.0
	v_fmac_f32_e32 v38, v40, v38
	v_mul_f32_e32 v40, v39, v38
	v_fma_f32 v41, -v37, v40, v39
	v_fmac_f32_e32 v40, v41, v38
	v_fma_f32 v37, -v37, v40, v39
	v_div_fmas_f32 v37, v37, v38, v40
	v_div_fixup_f32 v36, v37, v36, 1.0
	v_pk_mul_f32 v[32:33], v[32:33], v[36:37] op_sel_hi:[1,0]
	v_pk_mul_f32 v[30:31], v[30:31], v[36:37] op_sel_hi:[1,0]
	v_pk_mul_f32 v[20:21], v[20:21], v[36:37] op_sel_hi:[1,0]
	v_cvt_pk_bf16_f32 v30, v30, v31
	v_cvt_pk_bf16_f32 v31, v32, v33
	v_add_u32_e32 v32, s59, v35
	v_ashrrev_i32_e32 v33, 31, v32
	v_pk_mul_f32 v[18:19], v[18:19], v[36:37] op_sel_hi:[1,0]
	s_mov_b32 s9, s21
	v_readlane_b32 s28, v251, 54
	v_cvt_pk_bf16_f32 v18, v18, v19
	v_cvt_pk_bf16_f32 v19, v20, v21
	v_lshl_add_u64 v[20:21], v[32:33], 0, s[8:9]
	v_readlane_b32 s29, v251, 55
	v_lshlrev_b64 v[20:21], 6, v[20:21]
	v_lshl_add_u64 v[38:39], v[32:33], 0, s[20:21]
	v_lshl_add_u64 v[20:21], s[28:29], 0, v[20:21]
	v_lshl_add_u64 v[20:21], v[20:21], 0, v[0:1]
	global_store_dwordx2 v[20:21], v[18:19], off
	v_pk_mul_f32 v[18:19], v[24:25], v[36:37] op_sel_hi:[1,0]
	v_pk_mul_f32 v[20:21], v[22:23], v[36:37] op_sel_hi:[1,0]
	v_or_b32_e32 v22, s56, v34
	v_cvt_pk_bf16_f32 v20, v20, v21
	v_cvt_pk_bf16_f32 v21, v18, v19
	v_or_b32_e32 v18, 48, v22
	v_lshrrev_b32_e32 v18, 5, v18
	v_mul_lo_u32 v18, v18, s93
	v_mov_b32_e32 v19, v1
	v_lshl_add_u64 v[18:19], v[18:19], 0, v[32:33]
	v_lshlrev_b64 v[38:39], 6, v[38:39]
	v_bitop3_b32 v22, v22, 28, 48 bitop3:0xc8
	v_lshlrev_b64 v[18:19], 6, v[18:19]
	v_lshl_add_u64 v[38:39], s[28:29], 0, v[38:39]
	v_pk_mul_f32 v[28:29], v[28:29], v[36:37] op_sel_hi:[1,0]
	v_pk_mul_f32 v[26:27], v[26:27], v[36:37] op_sel_hi:[1,0]
	v_lshl_add_u64 v[18:19], s[28:29], 0, v[18:19]
	v_lshlrev_b32_e32 v22, 1, v22
	v_mov_b32_e32 v23, v1
	v_lshl_add_u64 v[38:39], v[38:39], 0, v[0:1]
	v_cvt_pk_bf16_f32 v26, v26, v27
	v_cvt_pk_bf16_f32 v27, v28, v29
	v_lshl_add_u64 v[18:19], v[18:19], 0, v[22:23]
	global_store_dwordx2 v[38:39], v[30:31], off
	global_store_dwordx2 v[38:39], v[26:27], off offset:32
	global_store_dwordx2 v[18:19], v[20:21], off
; DEVI unsigned pk2(float lo, float hi) { const f32x2_t v = {lo, hi}; const bf16x2_t b = __builtin_convertvector(v, bf16x2_t); return __builtin_bit_cast(unsigned, b); }
; DEVI size_t blk_off(int row, int col) { return ((size_t)(col >> 5) * MROWS + row) * 32 + (col & 31); }
; DEVI float xsum16(float x) { auto r = __builtin_amdgcn_permlane16_swap(__float_as_uint(x), __float_as_uint(x), false, false); return __uint_as_float(r[0]) + __uint_as_float(r[1]); }
; DEVI float xsum32(float x) { auto r = __builtin_amdgcn_permlane32_swap(__float_as_uint(x), __float_as_uint(x), false, false); return __uint_as_float(r[0]) + __uint_as_float(r[1]); }
; template <int DK, int QB, bool NA>
; DEVI void attn_item(const AttnArgs& a, unsigned char* smem) {
;     ...
;           f32x2 ls2 = {0.f, 0.f};
;           unsigned pw[2][4];
; #pragma unroll
;           for (int kb = 0; kb < 4; ++kb)
; #pragma unroll
;             for (int h = 0; h < 2; ++h) {
;               const f32x2 pe = {__builtin_amdgcn_exp2f(t[kb][h].x), __builtin_amdgcn_exp2f(t[kb][h].y)};
;               ls2 += pe;
;               pw[kb >> 1][(kb & 1) * 2 + h] = pk2(pe.x, pe.y);
;             }
;           l[qb] += ls2.x + ls2.y;
; #pragma unroll
;           for (int c = 0; c < 2; ++c) {
;             const u32x4 pv = (u32x4){pw[c][0], pw[c][1], pw[c][2], pw[c][3]};
;             pf[qb][c] = __builtin_bit_cast(bf16x8, pv);
;           }
;         }
;     ...
;   if (wact) {
; #pragma unroll
;     for (int qb = 0; qb < QB; ++qb) {
;       const float lt = xsum32(xsum16(l[qb]));
;       const float inv = 1.0f / lt;
;       const int qi = w * QB * 16 + qb * 16 + l16;
;       if (qi < a.nq) {
; #pragma unroll
;         for (int db = 0; db < 4; ++db) {
;           const f32x4 v = o[db][qb] * inv;
;           *(u32x2*)(a.O + blk_off(a.orow0 + qi, a.ocol0 + db * 16 + g * 4)) = (u32x2){pk2(v[0], v[1]), pk2(v[2], v[3])};
;         }
;       }
.LBB0_2334:
	s_or_b64 exec, exec, s[0:1]
	s_nop 1
	s_mov_b64 s[8:9], s[52:53]
	v_add_f32_e32 v18, v72, v68
	v_add_f32_e32 v19, v73, v69
	s_nop 0
	v_add_f32_e32 v18, v70, v18
	v_add_f32_e32 v19, v71, v19
	s_nop 0
	v_add_f32_e32 v18, v70, v18
	v_add_f32_e32 v19, v71, v19
	s_nop 0
	v_add_f32_e32 v18, v70, v18
	v_add_f32_e32 v19, v71, v19
	s_nop 0
	v_add_f32_e32 v18, v70, v18
	v_add_f32_e32 v19, v71, v19
	s_nop 0
	v_add_f32_e32 v18, v70, v18
	v_add_f32_e32 v19, v71, v19
	s_nop 0
	v_add_f32_e32 v18, v70, v18
	v_add_f32_e32 v19, v71, v19
	s_nop 0
	v_add_f32_e32 v18, v18, v19
	v_add_f32_e32 v18, v108, v18
	v_mov_b32_e32 v19, v18
	s_nop 1
	v_permlane16_swap_b32_e32 v18, v19
	v_add_f32_e32 v19, v18, v19
	v_mov_b32_e32 v20, v19
	v_or_b32_e32 v18, 16, v35
	s_nop 0
	v_permlane32_swap_b32_e32 v19, v20
	v_cmp_gt_i32_e32 vcc, s57, v18
	s_and_saveexec_b64 s[0:1], vcc
	s_cbranch_execz .LBB0_2336
	v_add_f32_e32 v19, v19, v20
	v_div_scale_f32 v20, s[8:9], v19, v19, 1.0
	v_rcp_f32_e32 v21, v20
	v_div_scale_f32 v22, vcc, 1.0, v19, 1.0
	v_readlane_b32 s8, v251, 54
	v_fma_f32 v23, -v20, v21, 1.0
	v_fmac_f32_e32 v21, v23, v21
	v_mul_f32_e32 v23, v22, v21
	v_fma_f32 v24, -v20, v23, v22
	v_fmac_f32_e32 v23, v24, v21
	v_fma_f32 v20, -v20, v23, v22
	v_div_fmas_f32 v20, v20, v21, v23
	v_div_fixup_f32 v20, v20, v19, 1.0
	v_pk_mul_f32 v[16:17], v[16:17], v[20:21] op_sel_hi:[1,0]
	v_pk_mul_f32 v[14:15], v[14:15], v[20:21] op_sel_hi:[1,0]
	v_pk_mul_f32 v[8:9], v[8:9], v[20:21] op_sel_hi:[1,0]
	v_cvt_pk_bf16_f32 v14, v14, v15
	v_cvt_pk_bf16_f32 v15, v16, v17
	v_add_u32_e32 v16, s59, v18
	v_ashrrev_i32_e32 v17, 31, v16
	v_lshl_add_u64 v[18:19], v[16:17], 0, s[20:21]
	v_pk_mul_f32 v[6:7], v[6:7], v[20:21] op_sel_hi:[1,0]
	s_add_i32 s20, s20, 0xc280
	v_cvt_pk_bf16_f32 v6, v6, v7
	v_cvt_pk_bf16_f32 v7, v8, v9
	v_lshl_add_u64 v[8:9], v[16:17], 0, s[20:21]
	v_lshlrev_b64 v[18:19], 6, v[18:19]
	v_readlane_b32 s9, v251, 55
	v_lshlrev_b64 v[8:9], 6, v[8:9]
	v_or3_b32 v64, s56, v34, 48
	v_lshl_add_u64 v[18:19], s[8:9], 0, v[18:19]
	v_lshl_add_u64 v[8:9], s[8:9], 0, v[8:9]
	v_lshl_add_u64 v[18:19], v[18:19], 0, v[0:1]
	v_lshl_add_u64 v[8:9], v[8:9], 0, v[0:1]
	v_lshrrev_b32_e32 v0, 5, v64
	v_pk_mul_f32 v[12:13], v[12:13], v[20:21] op_sel_hi:[1,0]
	v_pk_mul_f32 v[10:11], v[10:11], v[20:21] op_sel_hi:[1,0]
	v_pk_mul_f32 v[4:5], v[4:5], v[20:21] op_sel_hi:[1,0]
	v_pk_mul_f32 v[2:3], v[2:3], v[20:21] op_sel_hi:[1,0]
	v_mul_lo_u32 v0, v0, s93
	v_cvt_pk_bf16_f32 v10, v10, v11
	v_cvt_pk_bf16_f32 v11, v12, v13
	v_cvt_pk_bf16_f32 v60, v2, v3
	v_cvt_pk_bf16_f32 v61, v4, v5
	v_lshl_add_u64 v[62:63], v[0:1], 0, v[16:17]
	s_or_b64 s[8:9], s[52:53], exec
	global_store_dwordx2 v[18:19], v[14:15], off
	global_store_dwordx2 v[18:19], v[10:11], off offset:32
	global_store_dwordx2 v[8:9], v[6:7], off
